# sgemm_sample K loops: workgroup-cooperative LDS staging (full-row coalesced loads of the 16 A rows and 128 B rows in K=128 slabs, swizzled tiles, double-buffered, 3 slabs in flight); same MFMA order
# speedup vs baseline: 1.0253x; 1.0253x over previous
; template <int MODE>
; __device__ __forceinline__ void sgemm_sample(LAS unsigned char* lds, const bf16_t* A, const bf16_t* Bt, int K, const float* resid, float* out, bf16_t* xb, float* ssq_out, const float* ssq_in) {
;     ...
;     for (int uu = u; uu < 2048; uu += gridDim.x * 8) {
;         const int rt = uu >> 6, ct = uu & 63; const int row = NTOKP + rt * 16 + fr, col0 = ct * 16 + fq * 4;
;         const bf16_t* ap = A + (size_t)row * K + fq * 8; const bf16_t* bp = Bt + (size_t)(ct * 16 + fr) * K + fq * 8;
;         f32x4 acc = {0.f, 0.f, 0.f, 0.f};
; #pragma unroll 8
;         for (int ks = 0; ks < K / 32; ++ks) {
;             const bf16x8 a = *(const bf16x8*)(ap + ks * 32); const bf16x8 b = *(const bf16x8*)(bp + ks * 32);
;             acc = __builtin_amdgcn_mfma_f32_16x16x32_bf16(b, a, acc, 0, 0, 0);
;         }
.LBB0_894:
	s_and_b32 s6, s15, 63
	v_lshl_or_b32 v4, s6, 15, v21
	s_ashr_i32 s6, s3, 2
	s_and_b32 s6, s6, -16
	s_add_i32 s6, s6, 0x8000
	v_or_b32_e32 v12, s6, v17
	v_ashrrev_i32_e32 v13, 31, v12
	v_lshlrev_b64 v[8:9], 11, v[12:13]
	v_lshl_add_u64 v[10:11], v[6:7], 0, v[4:5]
	v_lshl_add_u64 v[14:15], v[6:7], 0, v[8:9]
	s_mov_b64 s[16:17], 0
	v_mov_b32_e32 v0, 0
	v_mov_b32_e32 v1, v5
	v_mov_b32_e32 v2, v5
	v_mov_b32_e32 v3, v5
	s_cmpk_lg_i32 s34, 0x100
	s_cbranch_scc1 .LBB0_895
	s_waitcnt vmcnt(0)
	s_lshr_b32 s100, s2, 3
	s_lshl_b32 s100, s100, 4
	s_add_i32 s100, s100, 0x8000
	s_mul_i32 s100, s100, 0x800
	s_add_u32 s96, s92, s100
	s_addc_u32 s97, s93, 0
	s_add_u32 s96, s96, 0x15780000
	s_addc_u32 s97, s97, 0
	s_and_b32 s100, s2, 7
	s_lshl_b32 s100, s100, 7
	s_mul_i32 s100, s100, 0x800
	s_add_u32 s98, s92, s100
	s_addc_u32 s99, s93, 0
	s_add_u32 s98, s98, 0x840000
	s_addc_u32 s99, s99, 0
	v_lshrrev_b32_e32 v172, 4, v200
	v_and_b32_e32 v173, 15, v200
	v_and_b32_e32 v174, 15, v172
	v_xor_b32_e32 v173, v173, v174
	v_lshlrev_b32_e32 v173, 4, v173
	s_mov_b32 s100, 0x800
	v_mad_u32_u24 v124, v172, s100, v173
	v_add_u32_e32 v125, 0x10000, v124
	v_add_u32_e32 v126, 0x20000, v124
	v_add_u32_e32 v127, 0x30000, v124
	v_mad_u32_u24 v128, v174, s100, v173
	v_lshlrev_b32_e32 v129, 4, v200
	v_add_u32_e32 v129, 1024, v129
	v_and_b32_e32 v130, 0xff, v200
	v_lshlrev_b32_e32 v130, 4, v130
	v_add_u32_e32 v130, 33792, v130
	v_and_b32_e32 v172, 15, v200
	v_bfe_u32 v173, v200, 4, 2
	v_and_b32_e32 v174, 3, v172
	v_xor_b32_e32 v173, v173, v174
	v_lshlrev_b32_e32 v173, 4, v173
	v_lshrrev_b32_e32 v174, 2, v172
	v_lshl_add_u32 v173, v174, 6, v173
	v_lshl_add_u32 v173, v172, 8, v173
	v_add_u32_e32 v131, 33792, v173
	v_lshrrev_b32_e32 v174, 6, v200
	v_lshlrev_b32_e32 v174, 12, v174
	v_add_u32_e32 v135, v173, v174
	v_add_u32_e32 v135, 1024, v135
	v_xor_b32_e32 v132, 0x40, v131
	v_xor_b32_e32 v136, 0x40, v135
	v_xor_b32_e32 v133, 0x80, v131
	v_xor_b32_e32 v137, 0x80, v135
	v_xor_b32_e32 v134, 0xc0, v131
	v_xor_b32_e32 v138, 0xc0, v135
	global_load_dwordx4 v[64:67], v124, s[98:99]
	global_load_dwordx4 v[68:71], v125, s[98:99]
	global_load_dwordx4 v[72:75], v126, s[98:99]
	global_load_dwordx4 v[76:79], v127, s[98:99]
	global_load_dwordx4 v[80:83], v128, s[96:97]
	s_add_u32 s98, s98, 0x100
	s_addc_u32 s99, s99, 0
	s_add_u32 s96, s96, 0x100
	s_addc_u32 s97, s97, 0
	global_load_dwordx4 v[84:87], v124, s[98:99]
	global_load_dwordx4 v[88:91], v125, s[98:99]
	global_load_dwordx4 v[92:95], v126, s[98:99]
	global_load_dwordx4 v[96:99], v127, s[98:99]
	global_load_dwordx4 v[100:103], v128, s[96:97]
	s_add_u32 s98, s98, 0x100
	s_addc_u32 s99, s99, 0
	s_add_u32 s96, s96, 0x100
	s_addc_u32 s97, s97, 0
	global_load_dwordx4 v[104:107], v124, s[98:99]
	global_load_dwordx4 v[108:111], v125, s[98:99]
	global_load_dwordx4 v[112:115], v126, s[98:99]
	global_load_dwordx4 v[116:119], v127, s[98:99]
	global_load_dwordx4 v[120:123], v128, s[96:97]
	s_add_u32 s98, s98, 0x100
	s_addc_u32 s99, s99, 0
	s_add_u32 s96, s96, 0x100
	s_addc_u32 s97, s97, 0
	s_waitcnt vmcnt(14)
	ds_write_b128 v129, v[64:67]
	s_waitcnt vmcnt(13)
	ds_write_b128 v129, v[68:71] offset:8192
	s_waitcnt vmcnt(12)
	ds_write_b128 v129, v[72:75] offset:16384
	s_waitcnt vmcnt(11)
	ds_write_b128 v129, v[76:79] offset:24576
	s_waitcnt vmcnt(10)
	ds_write_b128 v130, v[80:83]
	s_waitcnt lgkmcnt(0)
	s_barrier
	s_waitcnt vmcnt(9)
	ds_write_b128 v129, v[84:87] offset:36864
	s_waitcnt vmcnt(8)
	ds_write_b128 v129, v[88:91] offset:45056
	s_waitcnt vmcnt(7)
	ds_write_b128 v129, v[92:95] offset:53248
	s_waitcnt vmcnt(6)
	ds_write_b128 v129, v[96:99] offset:61440
	s_waitcnt vmcnt(5)
	ds_write_b128 v130, v[100:103] offset:36864
	global_load_dwordx4 v[64:67], v124, s[98:99]
	global_load_dwordx4 v[68:71], v125, s[98:99]
	global_load_dwordx4 v[72:75], v126, s[98:99]
	global_load_dwordx4 v[76:79], v127, s[98:99]
	global_load_dwordx4 v[80:83], v128, s[96:97]
	s_add_u32 s98, s98, 0x100
	s_addc_u32 s99, s99, 0
	s_add_u32 s96, s96, 0x100
	s_addc_u32 s97, s97, 0
	ds_read_b128 v[140:143], v135
	ds_read_b128 v[144:147], v131
	ds_read_b128 v[148:151], v136
	ds_read_b128 v[152:155], v132
	ds_read_b128 v[156:159], v137
	ds_read_b128 v[160:163], v133
	ds_read_b128 v[164:167], v138
	ds_read_b128 v[168:171], v134
	s_waitcnt lgkmcnt(6)
	v_mfma_f32_16x16x32_bf16 v[0:3], v[140:143], v[144:147], v[0:3]
	s_waitcnt lgkmcnt(4)
	v_mfma_f32_16x16x32_bf16 v[0:3], v[148:151], v[152:155], v[0:3]
	s_waitcnt lgkmcnt(2)
	v_mfma_f32_16x16x32_bf16 v[0:3], v[156:159], v[160:163], v[0:3]
	s_waitcnt lgkmcnt(0)
	v_mfma_f32_16x16x32_bf16 v[0:3], v[164:167], v[168:171], v[0:3]
	s_waitcnt lgkmcnt(0)
	s_barrier
	s_waitcnt vmcnt(9)
	ds_write_b128 v129, v[104:107]
	s_waitcnt vmcnt(8)
	ds_write_b128 v129, v[108:111] offset:8192
	s_waitcnt vmcnt(7)
	ds_write_b128 v129, v[112:115] offset:16384
	s_waitcnt vmcnt(6)
	ds_write_b128 v129, v[116:119] offset:24576
	s_waitcnt vmcnt(5)
	ds_write_b128 v130, v[120:123]
	global_load_dwordx4 v[84:87], v124, s[98:99]
	global_load_dwordx4 v[88:91], v125, s[98:99]
	global_load_dwordx4 v[92:95], v126, s[98:99]
	global_load_dwordx4 v[96:99], v127, s[98:99]
	global_load_dwordx4 v[100:103], v128, s[96:97]
	s_add_u32 s98, s98, 0x100
	s_addc_u32 s99, s99, 0
	s_add_u32 s96, s96, 0x100
	s_addc_u32 s97, s97, 0
	ds_read_b128 v[140:143], v135 offset:36864
	ds_read_b128 v[144:147], v131 offset:36864
	ds_read_b128 v[148:151], v136 offset:36864
	ds_read_b128 v[152:155], v132 offset:36864
	ds_read_b128 v[156:159], v137 offset:36864
	ds_read_b128 v[160:163], v133 offset:36864
	ds_read_b128 v[164:167], v138 offset:36864
	ds_read_b128 v[168:171], v134 offset:36864
	s_waitcnt lgkmcnt(6)
	v_mfma_f32_16x16x32_bf16 v[0:3], v[140:143], v[144:147], v[0:3]
	s_waitcnt lgkmcnt(4)
	v_mfma_f32_16x16x32_bf16 v[0:3], v[148:151], v[152:155], v[0:3]
	s_waitcnt lgkmcnt(2)
	v_mfma_f32_16x16x32_bf16 v[0:3], v[156:159], v[160:163], v[0:3]
	s_waitcnt lgkmcnt(0)
	v_mfma_f32_16x16x32_bf16 v[0:3], v[164:167], v[168:171], v[0:3]
	s_waitcnt lgkmcnt(0)
	s_barrier
; template <int MODE>
; __device__ __forceinline__ void sgemm_sample(LAS unsigned char* lds, const bf16_t* A, const bf16_t* Bt, int K, const float* resid, float* out, bf16_t* xb, float* ssq_out, const float* ssq_in) {
;     ...
; #pragma unroll 8
;         for (int ks = 0; ks < K / 32; ++ks) {
;             const bf16x8 a = *(const bf16x8*)(ap + ks * 32); const bf16x8 b = *(const bf16x8*)(bp + ks * 32);
;             acc = __builtin_amdgcn_mfma_f32_16x16x32_bf16(b, a, acc, 0, 0, 0);
;         }
	s_waitcnt vmcnt(9)
	ds_write_b128 v129, v[64:67] offset:36864
	s_waitcnt vmcnt(8)
	ds_write_b128 v129, v[68:71] offset:45056
	s_waitcnt vmcnt(7)
	ds_write_b128 v129, v[72:75] offset:53248
	s_waitcnt vmcnt(6)
	ds_write_b128 v129, v[76:79] offset:61440
	s_waitcnt vmcnt(5)
	ds_write_b128 v130, v[80:83] offset:36864
	global_load_dwordx4 v[104:107], v124, s[98:99]
	global_load_dwordx4 v[108:111], v125, s[98:99]
	global_load_dwordx4 v[112:115], v126, s[98:99]
	global_load_dwordx4 v[116:119], v127, s[98:99]
	global_load_dwordx4 v[120:123], v128, s[96:97]
	s_add_u32 s98, s98, 0x100
	s_addc_u32 s99, s99, 0
	s_add_u32 s96, s96, 0x100
	s_addc_u32 s97, s97, 0
	ds_read_b128 v[140:143], v135
	ds_read_b128 v[144:147], v131
	ds_read_b128 v[148:151], v136
	ds_read_b128 v[152:155], v132
	ds_read_b128 v[156:159], v137
	ds_read_b128 v[160:163], v133
	ds_read_b128 v[164:167], v138
	ds_read_b128 v[168:171], v134
	s_waitcnt lgkmcnt(6)
	v_mfma_f32_16x16x32_bf16 v[0:3], v[140:143], v[144:147], v[0:3]
	s_waitcnt lgkmcnt(4)
	v_mfma_f32_16x16x32_bf16 v[0:3], v[148:151], v[152:155], v[0:3]
	s_waitcnt lgkmcnt(2)
	v_mfma_f32_16x16x32_bf16 v[0:3], v[156:159], v[160:163], v[0:3]
	s_waitcnt lgkmcnt(0)
	v_mfma_f32_16x16x32_bf16 v[0:3], v[164:167], v[168:171], v[0:3]
	s_waitcnt lgkmcnt(0)
	s_barrier
	s_waitcnt vmcnt(9)
	ds_write_b128 v129, v[84:87]
	s_waitcnt vmcnt(8)
	ds_write_b128 v129, v[88:91] offset:8192
	s_waitcnt vmcnt(7)
	ds_write_b128 v129, v[92:95] offset:16384
	s_waitcnt vmcnt(6)
	ds_write_b128 v129, v[96:99] offset:24576
	s_waitcnt vmcnt(5)
	ds_write_b128 v130, v[100:103]
	global_load_dwordx4 v[64:67], v124, s[98:99]
	global_load_dwordx4 v[68:71], v125, s[98:99]
	global_load_dwordx4 v[72:75], v126, s[98:99]
	global_load_dwordx4 v[76:79], v127, s[98:99]
	global_load_dwordx4 v[80:83], v128, s[96:97]
	s_add_u32 s98, s98, 0x100
	s_addc_u32 s99, s99, 0
	s_add_u32 s96, s96, 0x100
	s_addc_u32 s97, s97, 0
	ds_read_b128 v[140:143], v135 offset:36864
	ds_read_b128 v[144:147], v131 offset:36864
	ds_read_b128 v[148:151], v136 offset:36864
	ds_read_b128 v[152:155], v132 offset:36864
	ds_read_b128 v[156:159], v137 offset:36864
	ds_read_b128 v[160:163], v133 offset:36864
	ds_read_b128 v[164:167], v138 offset:36864
	ds_read_b128 v[168:171], v134 offset:36864
	s_waitcnt lgkmcnt(6)
	v_mfma_f32_16x16x32_bf16 v[0:3], v[140:143], v[144:147], v[0:3]
	s_waitcnt lgkmcnt(4)
	v_mfma_f32_16x16x32_bf16 v[0:3], v[148:151], v[152:155], v[0:3]
	s_waitcnt lgkmcnt(2)
	v_mfma_f32_16x16x32_bf16 v[0:3], v[156:159], v[160:163], v[0:3]
	s_waitcnt lgkmcnt(0)
	v_mfma_f32_16x16x32_bf16 v[0:3], v[164:167], v[168:171], v[0:3]
	s_waitcnt lgkmcnt(0)
	s_barrier
	s_waitcnt vmcnt(9)
	ds_write_b128 v129, v[104:107] offset:36864
	s_waitcnt vmcnt(8)
	ds_write_b128 v129, v[108:111] offset:45056
	s_waitcnt vmcnt(7)
	ds_write_b128 v129, v[112:115] offset:53248
	s_waitcnt vmcnt(6)
	ds_write_b128 v129, v[116:119] offset:61440
	s_waitcnt vmcnt(5)
	ds_write_b128 v130, v[120:123] offset:36864
	global_load_dwordx4 v[84:87], v124, s[98:99]
	global_load_dwordx4 v[88:91], v125, s[98:99]
	global_load_dwordx4 v[92:95], v126, s[98:99]
	global_load_dwordx4 v[96:99], v127, s[98:99]
	global_load_dwordx4 v[100:103], v128, s[96:97]
	s_add_u32 s98, s98, 0x100
	s_addc_u32 s99, s99, 0
	s_add_u32 s96, s96, 0x100
	s_addc_u32 s97, s97, 0
	ds_read_b128 v[140:143], v135
	ds_read_b128 v[144:147], v131
	ds_read_b128 v[148:151], v136
	ds_read_b128 v[152:155], v132
	ds_read_b128 v[156:159], v137
	ds_read_b128 v[160:163], v133
	ds_read_b128 v[164:167], v138
	ds_read_b128 v[168:171], v134
	s_waitcnt lgkmcnt(6)
	v_mfma_f32_16x16x32_bf16 v[0:3], v[140:143], v[144:147], v[0:3]
	s_waitcnt lgkmcnt(4)
	v_mfma_f32_16x16x32_bf16 v[0:3], v[148:151], v[152:155], v[0:3]
	s_waitcnt lgkmcnt(2)
	v_mfma_f32_16x16x32_bf16 v[0:3], v[156:159], v[160:163], v[0:3]
	s_waitcnt lgkmcnt(0)
	v_mfma_f32_16x16x32_bf16 v[0:3], v[164:167], v[168:171], v[0:3]
	s_waitcnt lgkmcnt(0)
	s_barrier
	s_waitcnt vmcnt(9)
	ds_write_b128 v129, v[64:67]
	s_waitcnt vmcnt(8)
	ds_write_b128 v129, v[68:71] offset:8192
	s_waitcnt vmcnt(7)
	ds_write_b128 v129, v[72:75] offset:16384
	s_waitcnt vmcnt(6)
	ds_write_b128 v129, v[76:79] offset:24576
	s_waitcnt vmcnt(5)
	ds_write_b128 v130, v[80:83]
	ds_read_b128 v[140:143], v135 offset:36864
	ds_read_b128 v[144:147], v131 offset:36864
	ds_read_b128 v[148:151], v136 offset:36864
	ds_read_b128 v[152:155], v132 offset:36864
	ds_read_b128 v[156:159], v137 offset:36864
	ds_read_b128 v[160:163], v133 offset:36864
	ds_read_b128 v[164:167], v138 offset:36864
	ds_read_b128 v[168:171], v134 offset:36864
	s_waitcnt lgkmcnt(6)
	v_mfma_f32_16x16x32_bf16 v[0:3], v[140:143], v[144:147], v[0:3]
	s_waitcnt lgkmcnt(4)
	v_mfma_f32_16x16x32_bf16 v[0:3], v[148:151], v[152:155], v[0:3]
	s_waitcnt lgkmcnt(2)
	v_mfma_f32_16x16x32_bf16 v[0:3], v[156:159], v[160:163], v[0:3]
	s_waitcnt lgkmcnt(0)
	v_mfma_f32_16x16x32_bf16 v[0:3], v[164:167], v[168:171], v[0:3]
	s_waitcnt lgkmcnt(0)
	s_barrier
	s_waitcnt vmcnt(4)
	ds_write_b128 v129, v[84:87] offset:36864
	s_waitcnt vmcnt(3)
	ds_write_b128 v129, v[88:91] offset:45056
	s_waitcnt vmcnt(2)
	ds_write_b128 v129, v[92:95] offset:53248
	s_waitcnt vmcnt(1)
	ds_write_b128 v129, v[96:99] offset:61440
	s_waitcnt vmcnt(0)
	ds_write_b128 v130, v[100:103] offset:36864
	ds_read_b128 v[140:143], v135
	ds_read_b128 v[144:147], v131
	ds_read_b128 v[148:151], v136
	ds_read_b128 v[152:155], v132
	ds_read_b128 v[156:159], v137
	ds_read_b128 v[160:163], v133
	ds_read_b128 v[164:167], v138
	ds_read_b128 v[168:171], v134
	s_waitcnt lgkmcnt(6)
	v_mfma_f32_16x16x32_bf16 v[0:3], v[140:143], v[144:147], v[0:3]
	s_waitcnt lgkmcnt(4)
	v_mfma_f32_16x16x32_bf16 v[0:3], v[148:151], v[152:155], v[0:3]
	s_waitcnt lgkmcnt(2)
	v_mfma_f32_16x16x32_bf16 v[0:3], v[156:159], v[160:163], v[0:3]
	s_waitcnt lgkmcnt(0)
	v_mfma_f32_16x16x32_bf16 v[0:3], v[164:167], v[168:171], v[0:3]
	s_waitcnt lgkmcnt(0)
	s_barrier
	ds_read_b128 v[140:143], v135 offset:36864
	ds_read_b128 v[144:147], v131 offset:36864
	ds_read_b128 v[148:151], v136 offset:36864
	ds_read_b128 v[152:155], v132 offset:36864
	ds_read_b128 v[156:159], v137 offset:36864
	ds_read_b128 v[160:163], v133 offset:36864
	ds_read_b128 v[164:167], v138 offset:36864
	ds_read_b128 v[168:171], v134 offset:36864
	s_waitcnt lgkmcnt(6)
	v_mfma_f32_16x16x32_bf16 v[0:3], v[140:143], v[144:147], v[0:3]
	s_waitcnt lgkmcnt(4)
	v_mfma_f32_16x16x32_bf16 v[0:3], v[148:151], v[152:155], v[0:3]
	s_waitcnt lgkmcnt(2)
	v_mfma_f32_16x16x32_bf16 v[0:3], v[156:159], v[160:163], v[0:3]
	s_waitcnt lgkmcnt(0)
	v_mfma_f32_16x16x32_bf16 v[0:3], v[164:167], v[168:171], v[0:3]
	s_nop 7
	s_branch .Lsgx0_done
; #define LAS __attribute__((address_space(3)))
; __device__ __forceinline__ unsigned cvt_pk_bf16(float lo, float hi) { f32x2 f = {lo, hi}; bf16x2_t v = __builtin_convertvector(f, bf16x2_t); return __builtin_bit_cast(unsigned, v); }
; template <int MODE>
; __device__ __forceinline__ void sgemm_sample(LAS unsigned char* lds, const bf16_t* A, const bf16_t* Bt, int K, const float* resid, float* out, bf16_t* xb, float* ssq_out, const float* ssq_in) {
;     ...
; #pragma unroll 8
;         for (int ks = 0; ks < K / 32; ++ks) {
;             const bf16x8 a = *(const bf16x8*)(ap + ks * 32); const bf16x8 b = *(const bf16x8*)(bp + ks * 32);
;             acc = __builtin_amdgcn_mfma_f32_16x16x32_bf16(b, a, acc, 0, 0, 0);
;         }
;         if (MODE == 0) {
;             const f32x4 x = *(const f32x4*)(resid + (size_t)(row - NTOKP) * D + col0) + acc;
;             *(f32x4*)(out + (size_t)row * D + col0) = x;
;             if (xb) { u32x2 wv; wv.x = cvt_pk_bf16(x[0], x[1]); wv.y = cvt_pk_bf16(x[2], x[3]); *(u32x2*)(xb + (size_t)row * D + col0) = wv; }
;             if (ssq_out) {
;                 float ss = (x[0] * x[0] + x[1] * x[1]) + (x[2] * x[2] + x[3] * x[3]); ss += __shfl_xor(ss, 16); ss += __shfl_xor(ss, 32);
;                 if (fq == 0) *(LAS float*)(lds + (w * 16 + fr) * 4) = ss;
;                 __syncthreads();
;                 if (tid < 16) { float t = 0.f;
; #pragma unroll
;                     for (int i = 0; i < 8; ++i) t += *(const LAS float*)(lds + (i * 16 + tid) * 4);
;                     const int g = (uu & 63) >> 3; float* sp = ssq_out + (size_t)(NTOKP + rt * 16 + tid) * 16; sp[g] = t; sp[8 + g] = 0.f; }
;                 __syncthreads();
;             }
.LBB0_895:
	v_lshl_add_u64 v[24:25], v[14:15], 0, s[16:17]
	v_add_co_u32_e32 v60, vcc, 0x15780000, v24
	v_lshl_add_u64 v[26:27], v[10:11], 0, s[16:17]
	s_nop 0
	v_addc_co_u32_e32 v61, vcc, 0, v25, vcc
	v_add_co_u32_e32 v62, vcc, 0x840000, v26
	s_add_u32 s16, s16, 0x200
	s_nop 0
	v_addc_co_u32_e32 v63, vcc, 0, v27, vcc
	global_load_dwordx4 v[24:27], v[60:61], off
	global_load_dwordx4 v[28:31], v[60:61], off offset:64
	global_load_dwordx4 v[32:35], v[60:61], off offset:128
	global_load_dwordx4 v[36:39], v[60:61], off offset:192
	global_load_dwordx4 v[40:43], v[60:61], off offset:256
	global_load_dwordx4 v[44:47], v[62:63], off
	global_load_dwordx4 v[48:51], v[62:63], off offset:64
	global_load_dwordx4 v[52:55], v[62:63], off offset:128
	global_load_dwordx4 v[56:59], v[62:63], off offset:192
	s_addc_u32 s17, s17, 0
	s_cmpk_eq_i32 s16, 0x800
	s_waitcnt vmcnt(3)
	v_mfma_f32_16x16x32_bf16 v[0:3], v[44:47], v[24:27], v[0:3]
	global_load_dwordx4 v[24:27], v[62:63], off offset:256
	s_waitcnt vmcnt(3)
	v_mfma_f32_16x16x32_bf16 v[0:3], v[48:51], v[28:31], v[0:3]
	global_load_dwordx4 v[28:31], v[62:63], off offset:320
	s_waitcnt vmcnt(3)
	v_mfma_f32_16x16x32_bf16 v[0:3], v[52:55], v[32:35], v[0:3]
	global_load_dwordx4 v[32:35], v[60:61], off offset:320
	s_waitcnt vmcnt(3)
	v_mfma_f32_16x16x32_bf16 v[0:3], v[56:59], v[36:39], v[0:3]
	global_load_dwordx4 v[36:39], v[62:63], off offset:384
	global_load_dwordx4 v[44:47], v[60:61], off offset:384
	s_waitcnt vmcnt(4)
	v_mfma_f32_16x16x32_bf16 v[0:3], v[24:27], v[40:43], v[0:3]
	global_load_dwordx4 v[24:27], v[62:63], off offset:448
	s_waitcnt vmcnt(3)
	v_mfma_f32_16x16x32_bf16 v[0:3], v[28:31], v[32:35], v[0:3]
	global_load_dwordx4 v[28:31], v[60:61], off offset:448
	s_waitcnt vmcnt(2)
	v_mfma_f32_16x16x32_bf16 v[0:3], v[36:39], v[44:47], v[0:3]
	s_waitcnt vmcnt(0)
	v_mfma_f32_16x16x32_bf16 v[0:3], v[24:27], v[28:31], v[0:3]
	s_cbranch_scc0 .LBB0_895
.Lsgx0_done:
	s_and_b32 s18, s3, 63
	v_lshl_or_b32 v24, s18, 4, v18
	v_lshlrev_b64 v[14:15], 12, v[12:13]
	v_lshl_add_u64 v[10:11], s[40:41], 0, v[14:15]
	v_lshlrev_b32_e32 v4, 2, v24
	v_lshl_add_u64 v[10:11], v[10:11], 0, v[4:5]
	v_add_co_u32_e32 v10, vcc, 0xf8000000, v10
	v_lshl_add_u64 v[14:15], s[90:91], 0, v[14:15]
	s_nop 0
	v_addc_co_u32_e32 v11, vcc, -1, v11, vcc
	global_load_dwordx4 v[10:13], v[10:11], off
	s_waitcnt vmcnt(0)
	v_pk_add_f32 v[2:3], v[2:3], v[12:13]
	v_pk_add_f32 v[0:1], v[0:1], v[10:11]
	v_mul_f32_e32 v11, v3, v3
	v_mul_f32_e32 v10, v1, v1
	v_fmac_f32_e32 v10, v0, v0
	v_fmac_f32_e32 v11, v2, v2
	v_add_f32_e32 v12, v10, v11
	ds_bpermute_b32 v13, v19, v12
	v_lshl_add_u64 v[10:11], v[14:15], 0, v[4:5]
	global_store_dwordx4 v[10:11], v[0:3], off
	v_cvt_pk_bf16_f32 v10, v0, v1
	v_cvt_pk_bf16_f32 v11, v2, v3
	s_waitcnt lgkmcnt(0)
	v_add_f32_e32 v0, v12, v13
	ds_bpermute_b32 v1, v20, v0
	v_lshl_add_u64 v[2:3], s[10:11], 0, v[8:9]
	v_lshlrev_b32_e32 v4, 1, v24
	v_lshl_add_u64 v[2:3], v[2:3], 0, v[4:5]
	global_store_dwordx2 v[2:3], v[10:11], off
	s_and_saveexec_b64 s[16:17], s[0:1]
	s_cbranch_execz .LBB0_898
	s_waitcnt lgkmcnt(0)
	v_add_f32_e32 v0, v0, v1
	ds_write_b32 v22, v0

; template <int MODE>
; __device__ __forceinline__ void sgemm_sample(LAS unsigned char* lds, const bf16_t* A, const bf16_t* Bt, int K, const float* resid, float* out, bf16_t* xb, float* ssq_out, const float* ssq_in) {
;     ...
;     for (int uu = u; uu < 2048; uu += gridDim.x * 8) {
;         const int rt = uu >> 6, ct = uu & 63; const int row = NTOKP + rt * 16 + fr, col0 = ct * 16 + fq * 4;
;         const bf16_t* ap = A + (size_t)row * K + fq * 8; const bf16_t* bp = Bt + (size_t)(ct * 16 + fr) * K + fq * 8;
;         f32x4 acc = {0.f, 0.f, 0.f, 0.f};
; #pragma unroll 8
;         for (int ks = 0; ks < K / 32; ++ks) {
;             const bf16x8 a = *(const bf16x8*)(ap + ks * 32); const bf16x8 b = *(const bf16x8*)(bp + ks * 32);
;             acc = __builtin_amdgcn_mfma_f32_16x16x32_bf16(b, a, acc, 0, 0, 0);
;         }
.LBB0_999:
	s_lshl_b32 s0, s7, 11
	s_and_b32 s0, s0, 0x1f8000
	v_lshl_or_b32 v4, v18, 1, s0
	s_ashr_i32 s0, s3, 2
	s_and_b32 s0, s0, -16
	v_add_u32_e32 v10, s0, v16
	v_ashrrev_i32_e32 v11, 31, v10
	v_lshlrev_b64 v[8:9], 11, v[10:11]
	v_lshl_add_u64 v[12:13], v[6:7], 0, v[4:5]
	v_lshl_add_u64 v[14:15], v[6:7], 0, v[8:9]
	s_mov_b64 s[0:1], 0
	v_mov_b32_e32 v0, 0
	v_mov_b32_e32 v1, v5
	v_mov_b32_e32 v2, v5
	v_mov_b32_e32 v3, v5
	s_cmpk_lg_i32 s34, 0x100
	s_cbranch_scc1 .LBB0_1000
	s_waitcnt vmcnt(0)
	s_lshr_b32 s100, s2, 3
	s_lshl_b32 s100, s100, 4
	s_add_i32 s100, s100, 0x8000
	s_mul_i32 s100, s100, 0x800
	s_add_u32 s96, s92, s100
	s_addc_u32 s97, s93, 0
	s_add_u32 s96, s96, 0xa4c0000
	s_addc_u32 s97, s97, 0
	s_and_b32 s100, s2, 7
	s_lshl_b32 s100, s100, 7
	s_mul_i32 s100, s100, 0x800
	s_add_u32 s98, s92, s100
	s_addc_u32 s99, s93, 0
	s_add_u32 s98, s98, 0xa40000
	s_addc_u32 s99, s99, 0
	v_lshrrev_b32_e32 v172, 4, v200
	v_and_b32_e32 v173, 15, v200
	v_and_b32_e32 v174, 15, v172
	v_xor_b32_e32 v173, v173, v174
	v_lshlrev_b32_e32 v173, 4, v173
	s_mov_b32 s100, 0x800
	v_mad_u32_u24 v124, v172, s100, v173
	v_add_u32_e32 v125, 0x10000, v124
	v_add_u32_e32 v126, 0x20000, v124
	v_add_u32_e32 v127, 0x30000, v124
	v_mad_u32_u24 v128, v174, s100, v173
	v_lshlrev_b32_e32 v129, 4, v200
	v_add_u32_e32 v129, 1024, v129
	v_and_b32_e32 v130, 0xff, v200
	v_lshlrev_b32_e32 v130, 4, v130
	v_add_u32_e32 v130, 33792, v130
	v_and_b32_e32 v172, 15, v200
	v_bfe_u32 v173, v200, 4, 2
	v_and_b32_e32 v174, 3, v172
	v_xor_b32_e32 v173, v173, v174
	v_lshlrev_b32_e32 v173, 4, v173
	v_lshrrev_b32_e32 v174, 2, v172
	v_lshl_add_u32 v173, v174, 6, v173
	v_lshl_add_u32 v173, v172, 8, v173
	v_add_u32_e32 v131, 33792, v173
	v_lshrrev_b32_e32 v174, 6, v200
	v_lshlrev_b32_e32 v174, 12, v174
	v_add_u32_e32 v135, v173, v174
	v_add_u32_e32 v135, 1024, v135
	v_xor_b32_e32 v132, 0x40, v131
	v_xor_b32_e32 v136, 0x40, v135
	v_xor_b32_e32 v133, 0x80, v131
	v_xor_b32_e32 v137, 0x80, v135
	v_xor_b32_e32 v134, 0xc0, v131
	v_xor_b32_e32 v138, 0xc0, v135
	global_load_dwordx4 v[64:67], v124, s[98:99]
	global_load_dwordx4 v[68:71], v125, s[98:99]
	global_load_dwordx4 v[72:75], v126, s[98:99]
	global_load_dwordx4 v[76:79], v127, s[98:99]
	global_load_dwordx4 v[80:83], v128, s[96:97]
	s_add_u32 s98, s98, 0x100
	s_addc_u32 s99, s99, 0
	s_add_u32 s96, s96, 0x100
	s_addc_u32 s97, s97, 0
	global_load_dwordx4 v[84:87], v124, s[98:99]
	global_load_dwordx4 v[88:91], v125, s[98:99]
	global_load_dwordx4 v[92:95], v126, s[98:99]
	global_load_dwordx4 v[96:99], v127, s[98:99]
	global_load_dwordx4 v[100:103], v128, s[96:97]
	s_add_u32 s98, s98, 0x100
	s_addc_u32 s99, s99, 0
	s_add_u32 s96, s96, 0x100
	s_addc_u32 s97, s97, 0
	global_load_dwordx4 v[104:107], v124, s[98:99]
	global_load_dwordx4 v[108:111], v125, s[98:99]
	global_load_dwordx4 v[112:115], v126, s[98:99]
	global_load_dwordx4 v[116:119], v127, s[98:99]
	global_load_dwordx4 v[120:123], v128, s[96:97]
	s_add_u32 s98, s98, 0x100
	s_addc_u32 s99, s99, 0
	s_add_u32 s96, s96, 0x100
	s_addc_u32 s97, s97, 0
	s_waitcnt vmcnt(14)
	ds_write_b128 v129, v[64:67]
	s_waitcnt vmcnt(13)
	ds_write_b128 v129, v[68:71] offset:8192
	s_waitcnt vmcnt(12)
	ds_write_b128 v129, v[72:75] offset:16384
	s_waitcnt vmcnt(11)
	ds_write_b128 v129, v[76:79] offset:24576
	s_waitcnt vmcnt(10)
	ds_write_b128 v130, v[80:83]
	s_waitcnt lgkmcnt(0)
	s_barrier
	s_waitcnt vmcnt(9)
	ds_write_b128 v129, v[84:87] offset:36864
	s_waitcnt vmcnt(8)
	ds_write_b128 v129, v[88:91] offset:45056
	s_waitcnt vmcnt(7)
	ds_write_b128 v129, v[92:95] offset:53248
	s_waitcnt vmcnt(6)
	ds_write_b128 v129, v[96:99] offset:61440
	s_waitcnt vmcnt(5)
	ds_write_b128 v130, v[100:103] offset:36864
	global_load_dwordx4 v[64:67], v124, s[98:99]
	global_load_dwordx4 v[68:71], v125, s[98:99]
	global_load_dwordx4 v[72:75], v126, s[98:99]
	global_load_dwordx4 v[76:79], v127, s[98:99]
	global_load_dwordx4 v[80:83], v128, s[96:97]
	s_add_u32 s98, s98, 0x100
	s_addc_u32 s99, s99, 0
	s_add_u32 s96, s96, 0x100
	s_addc_u32 s97, s97, 0
	ds_read_b128 v[140:143], v135
	ds_read_b128 v[144:147], v131
	ds_read_b128 v[148:151], v136
	ds_read_b128 v[152:155], v132
	ds_read_b128 v[156:159], v137
	ds_read_b128 v[160:163], v133
	ds_read_b128 v[164:167], v138
	ds_read_b128 v[168:171], v134
	s_waitcnt lgkmcnt(6)
	v_mfma_f32_16x16x32_bf16 v[0:3], v[140:143], v[144:147], v[0:3]
	s_waitcnt lgkmcnt(4)
	v_mfma_f32_16x16x32_bf16 v[0:3], v[148:151], v[152:155], v[0:3]
	s_waitcnt lgkmcnt(2)
	v_mfma_f32_16x16x32_bf16 v[0:3], v[156:159], v[160:163], v[0:3]
	s_waitcnt lgkmcnt(0)
	v_mfma_f32_16x16x32_bf16 v[0:3], v[164:167], v[168:171], v[0:3]
	s_waitcnt lgkmcnt(0)
	s_barrier
	s_waitcnt vmcnt(9)
	ds_write_b128 v129, v[104:107]
	s_waitcnt vmcnt(8)
	ds_write_b128 v129, v[108:111] offset:8192
	s_waitcnt vmcnt(7)
	ds_write_b128 v129, v[112:115] offset:16384
	s_waitcnt vmcnt(6)
	ds_write_b128 v129, v[116:119] offset:24576
	s_waitcnt vmcnt(5)
	ds_write_b128 v130, v[120:123]
	global_load_dwordx4 v[84:87], v124, s[98:99]
	global_load_dwordx4 v[88:91], v125, s[98:99]
	global_load_dwordx4 v[92:95], v126, s[98:99]
	global_load_dwordx4 v[96:99], v127, s[98:99]
	global_load_dwordx4 v[100:103], v128, s[96:97]
	s_add_u32 s98, s98, 0x100
	s_addc_u32 s99, s99, 0
	s_add_u32 s96, s96, 0x100
	s_addc_u32 s97, s97, 0
	ds_read_b128 v[140:143], v135 offset:36864
	ds_read_b128 v[144:147], v131 offset:36864
	ds_read_b128 v[148:151], v136 offset:36864
	ds_read_b128 v[152:155], v132 offset:36864
	ds_read_b128 v[156:159], v137 offset:36864
	ds_read_b128 v[160:163], v133 offset:36864
	ds_read_b128 v[164:167], v138 offset:36864
	ds_read_b128 v[168:171], v134 offset:36864
	s_waitcnt lgkmcnt(6)
	v_mfma_f32_16x16x32_bf16 v[0:3], v[140:143], v[144:147], v[0:3]
	s_waitcnt lgkmcnt(4)
	v_mfma_f32_16x16x32_bf16 v[0:3], v[148:151], v[152:155], v[0:3]
	s_waitcnt lgkmcnt(2)
	v_mfma_f32_16x16x32_bf16 v[0:3], v[156:159], v[160:163], v[0:3]
	s_waitcnt lgkmcnt(0)
	v_mfma_f32_16x16x32_bf16 v[0:3], v[164:167], v[168:171], v[0:3]
	s_waitcnt lgkmcnt(0)
	s_barrier
; template <int MODE>
; __device__ __forceinline__ void sgemm_sample(LAS unsigned char* lds, const bf16_t* A, const bf16_t* Bt, int K, const float* resid, float* out, bf16_t* xb, float* ssq_out, const float* ssq_in) {
;     ...
; #pragma unroll 8
;         for (int ks = 0; ks < K / 32; ++ks) {
;             const bf16x8 a = *(const bf16x8*)(ap + ks * 32); const bf16x8 b = *(const bf16x8*)(bp + ks * 32);
;             acc = __builtin_amdgcn_mfma_f32_16x16x32_bf16(b, a, acc, 0, 0, 0);
;         }
	s_waitcnt vmcnt(9)
	ds_write_b128 v129, v[64:67] offset:36864
	s_waitcnt vmcnt(8)
	ds_write_b128 v129, v[68:71] offset:45056
	s_waitcnt vmcnt(7)
	ds_write_b128 v129, v[72:75] offset:53248
	s_waitcnt vmcnt(6)
	ds_write_b128 v129, v[76:79] offset:61440
	s_waitcnt vmcnt(5)
	ds_write_b128 v130, v[80:83] offset:36864
	global_load_dwordx4 v[104:107], v124, s[98:99]
	global_load_dwordx4 v[108:111], v125, s[98:99]
	global_load_dwordx4 v[112:115], v126, s[98:99]
	global_load_dwordx4 v[116:119], v127, s[98:99]
	global_load_dwordx4 v[120:123], v128, s[96:97]
	s_add_u32 s98, s98, 0x100
	s_addc_u32 s99, s99, 0
	s_add_u32 s96, s96, 0x100
	s_addc_u32 s97, s97, 0
	ds_read_b128 v[140:143], v135
	ds_read_b128 v[144:147], v131
	ds_read_b128 v[148:151], v136
	ds_read_b128 v[152:155], v132
	ds_read_b128 v[156:159], v137
	ds_read_b128 v[160:163], v133
	ds_read_b128 v[164:167], v138
	ds_read_b128 v[168:171], v134
	s_waitcnt lgkmcnt(6)
	v_mfma_f32_16x16x32_bf16 v[0:3], v[140:143], v[144:147], v[0:3]
	s_waitcnt lgkmcnt(4)
	v_mfma_f32_16x16x32_bf16 v[0:3], v[148:151], v[152:155], v[0:3]
	s_waitcnt lgkmcnt(2)
	v_mfma_f32_16x16x32_bf16 v[0:3], v[156:159], v[160:163], v[0:3]
	s_waitcnt lgkmcnt(0)
	v_mfma_f32_16x16x32_bf16 v[0:3], v[164:167], v[168:171], v[0:3]
	s_waitcnt lgkmcnt(0)
	s_barrier
	s_waitcnt vmcnt(9)
	ds_write_b128 v129, v[84:87]
	s_waitcnt vmcnt(8)
	ds_write_b128 v129, v[88:91] offset:8192
	s_waitcnt vmcnt(7)
	ds_write_b128 v129, v[92:95] offset:16384
	s_waitcnt vmcnt(6)
	ds_write_b128 v129, v[96:99] offset:24576
	s_waitcnt vmcnt(5)
	ds_write_b128 v130, v[100:103]
	global_load_dwordx4 v[64:67], v124, s[98:99]
	global_load_dwordx4 v[68:71], v125, s[98:99]
	global_load_dwordx4 v[72:75], v126, s[98:99]
	global_load_dwordx4 v[76:79], v127, s[98:99]
	global_load_dwordx4 v[80:83], v128, s[96:97]
	s_add_u32 s98, s98, 0x100
	s_addc_u32 s99, s99, 0
	s_add_u32 s96, s96, 0x100
	s_addc_u32 s97, s97, 0
	ds_read_b128 v[140:143], v135 offset:36864
	ds_read_b128 v[144:147], v131 offset:36864
	ds_read_b128 v[148:151], v136 offset:36864
	ds_read_b128 v[152:155], v132 offset:36864
	ds_read_b128 v[156:159], v137 offset:36864
	ds_read_b128 v[160:163], v133 offset:36864
	ds_read_b128 v[164:167], v138 offset:36864
	ds_read_b128 v[168:171], v134 offset:36864
	s_waitcnt lgkmcnt(6)
	v_mfma_f32_16x16x32_bf16 v[0:3], v[140:143], v[144:147], v[0:3]
	s_waitcnt lgkmcnt(4)
	v_mfma_f32_16x16x32_bf16 v[0:3], v[148:151], v[152:155], v[0:3]
	s_waitcnt lgkmcnt(2)
	v_mfma_f32_16x16x32_bf16 v[0:3], v[156:159], v[160:163], v[0:3]
	s_waitcnt lgkmcnt(0)
	v_mfma_f32_16x16x32_bf16 v[0:3], v[164:167], v[168:171], v[0:3]
	s_waitcnt lgkmcnt(0)
	s_barrier
	s_waitcnt vmcnt(9)
	ds_write_b128 v129, v[104:107] offset:36864
	s_waitcnt vmcnt(8)
	ds_write_b128 v129, v[108:111] offset:45056
	s_waitcnt vmcnt(7)
	ds_write_b128 v129, v[112:115] offset:53248
	s_waitcnt vmcnt(6)
	ds_write_b128 v129, v[116:119] offset:61440
	s_waitcnt vmcnt(5)
	ds_write_b128 v130, v[120:123] offset:36864
	global_load_dwordx4 v[84:87], v124, s[98:99]
	global_load_dwordx4 v[88:91], v125, s[98:99]
	global_load_dwordx4 v[92:95], v126, s[98:99]
	global_load_dwordx4 v[96:99], v127, s[98:99]
	global_load_dwordx4 v[100:103], v128, s[96:97]
	s_add_u32 s98, s98, 0x100
	s_addc_u32 s99, s99, 0
	s_add_u32 s96, s96, 0x100
	s_addc_u32 s97, s97, 0
	ds_read_b128 v[140:143], v135
	ds_read_b128 v[144:147], v131
	ds_read_b128 v[148:151], v136
	ds_read_b128 v[152:155], v132
	ds_read_b128 v[156:159], v137
	ds_read_b128 v[160:163], v133
	ds_read_b128 v[164:167], v138
	ds_read_b128 v[168:171], v134
	s_waitcnt lgkmcnt(6)
	v_mfma_f32_16x16x32_bf16 v[0:3], v[140:143], v[144:147], v[0:3]
	s_waitcnt lgkmcnt(4)
	v_mfma_f32_16x16x32_bf16 v[0:3], v[148:151], v[152:155], v[0:3]
	s_waitcnt lgkmcnt(2)
	v_mfma_f32_16x16x32_bf16 v[0:3], v[156:159], v[160:163], v[0:3]
	s_waitcnt lgkmcnt(0)
	v_mfma_f32_16x16x32_bf16 v[0:3], v[164:167], v[168:171], v[0:3]
	s_waitcnt lgkmcnt(0)
	s_barrier
	s_waitcnt vmcnt(9)
	ds_write_b128 v129, v[64:67]
	s_waitcnt vmcnt(8)
	ds_write_b128 v129, v[68:71] offset:8192
	s_waitcnt vmcnt(7)
	ds_write_b128 v129, v[72:75] offset:16384
	s_waitcnt vmcnt(6)
	ds_write_b128 v129, v[76:79] offset:24576
	s_waitcnt vmcnt(5)
	ds_write_b128 v130, v[80:83]
	ds_read_b128 v[140:143], v135 offset:36864
	ds_read_b128 v[144:147], v131 offset:36864
	ds_read_b128 v[148:151], v136 offset:36864
	ds_read_b128 v[152:155], v132 offset:36864
	ds_read_b128 v[156:159], v137 offset:36864
	ds_read_b128 v[160:163], v133 offset:36864
	ds_read_b128 v[164:167], v138 offset:36864
	ds_read_b128 v[168:171], v134 offset:36864
	s_waitcnt lgkmcnt(6)
	v_mfma_f32_16x16x32_bf16 v[0:3], v[140:143], v[144:147], v[0:3]
	s_waitcnt lgkmcnt(4)
	v_mfma_f32_16x16x32_bf16 v[0:3], v[148:151], v[152:155], v[0:3]
	s_waitcnt lgkmcnt(2)
	v_mfma_f32_16x16x32_bf16 v[0:3], v[156:159], v[160:163], v[0:3]
	s_waitcnt lgkmcnt(0)
	v_mfma_f32_16x16x32_bf16 v[0:3], v[164:167], v[168:171], v[0:3]
	s_waitcnt lgkmcnt(0)
	s_barrier
	s_waitcnt vmcnt(4)
	ds_write_b128 v129, v[84:87] offset:36864
	s_waitcnt vmcnt(3)
	ds_write_b128 v129, v[88:91] offset:45056
	s_waitcnt vmcnt(2)
	ds_write_b128 v129, v[92:95] offset:53248
	s_waitcnt vmcnt(1)
	ds_write_b128 v129, v[96:99] offset:61440
	s_waitcnt vmcnt(0)
	ds_write_b128 v130, v[100:103] offset:36864
	ds_read_b128 v[140:143], v135
	ds_read_b128 v[144:147], v131
	ds_read_b128 v[148:151], v136
	ds_read_b128 v[152:155], v132
	ds_read_b128 v[156:159], v137
	ds_read_b128 v[160:163], v133
	ds_read_b128 v[164:167], v138
	ds_read_b128 v[168:171], v134
	s_waitcnt lgkmcnt(6)
	v_mfma_f32_16x16x32_bf16 v[0:3], v[140:143], v[144:147], v[0:3]
	s_waitcnt lgkmcnt(4)
	v_mfma_f32_16x16x32_bf16 v[0:3], v[148:151], v[152:155], v[0:3]
	s_waitcnt lgkmcnt(2)
	v_mfma_f32_16x16x32_bf16 v[0:3], v[156:159], v[160:163], v[0:3]
	s_waitcnt lgkmcnt(0)
	v_mfma_f32_16x16x32_bf16 v[0:3], v[164:167], v[168:171], v[0:3]
	s_waitcnt lgkmcnt(0)
	s_barrier
	ds_read_b128 v[140:143], v135 offset:36864
	ds_read_b128 v[144:147], v131 offset:36864
	ds_read_b128 v[148:151], v136 offset:36864
	ds_read_b128 v[152:155], v132 offset:36864
	ds_read_b128 v[156:159], v137 offset:36864
	ds_read_b128 v[160:163], v133 offset:36864
	ds_read_b128 v[164:167], v138 offset:36864
	ds_read_b128 v[168:171], v134 offset:36864
	s_waitcnt lgkmcnt(6)
	v_mfma_f32_16x16x32_bf16 v[0:3], v[140:143], v[144:147], v[0:3]
	s_waitcnt lgkmcnt(4)
	v_mfma_f32_16x16x32_bf16 v[0:3], v[148:151], v[152:155], v[0:3]
	s_waitcnt lgkmcnt(2)
	v_mfma_f32_16x16x32_bf16 v[0:3], v[156:159], v[160:163], v[0:3]
	s_waitcnt lgkmcnt(0)
	v_mfma_f32_16x16x32_bf16 v[0:3], v[164:167], v[168:171], v[0:3]
	s_nop 7
	s_branch .Lsgx1_done
; #define LAS __attribute__((address_space(3)))
; __device__ __forceinline__ unsigned cvt_pk_bf16(float lo, float hi) { f32x2 f = {lo, hi}; bf16x2_t v = __builtin_convertvector(f, bf16x2_t); return __builtin_bit_cast(unsigned, v); }
; __device__ __forceinline__ float rs_from_parts(const float* sp) {
;     const f32x4 a = *(const f32x4*)sp, b = *(const f32x4*)(sp + 4), c = *(const f32x4*)(sp + 8), d = *(const f32x4*)(sp + 12);
;     const float s = ((a[0] + a[1]) + (a[2] + a[3])) + ((b[0] + b[1]) + (b[2] + b[3])) + ((c[0] + c[1]) + (c[2] + c[3])) + ((d[0] + d[1]) + (d[2] + d[3]));
;     return rsqrtf(s * (1.0f / 1024.0f) + 1e-6f);
; }
; template <int MODE>
; __device__ __forceinline__ void sgemm_sample(LAS unsigned char* lds, const bf16_t* A, const bf16_t* Bt, int K, const float* resid, float* out, bf16_t* xb, float* ssq_out, const float* ssq_in) {
;     ...
; #pragma unroll 8
;         for (int ks = 0; ks < K / 32; ++ks) {
;             const bf16x8 a = *(const bf16x8*)(ap + ks * 32); const bf16x8 b = *(const bf16x8*)(bp + ks * 32);
;             acc = __builtin_amdgcn_mfma_f32_16x16x32_bf16(b, a, acc, 0, 0, 0);
;         }
;         if (MODE == 0) {
;             const f32x4 x = *(const f32x4*)(resid + (size_t)(row - NTOKP) * D + col0) + acc;
;             *(f32x4*)(out + (size_t)row * D + col0) = x;
;             if (xb) { u32x2 wv; wv.x = cvt_pk_bf16(x[0], x[1]); wv.y = cvt_pk_bf16(x[2], x[3]); *(u32x2*)(xb + (size_t)row * D + col0) = wv; }
;             if (ssq_out) {
;                 float ss = (x[0] * x[0] + x[1] * x[1]) + (x[2] * x[2] + x[3] * x[3]); ss += __shfl_xor(ss, 16); ss += __shfl_xor(ss, 32);
;                 if (fq == 0) *(LAS float*)(lds + (w * 16 + fr) * 4) = ss;
;                 __syncthreads();
;                 if (tid < 16) { float t = 0.f;
; #pragma unroll
;                     for (int i = 0; i < 8; ++i) t += *(const LAS float*)(lds + (i * 16 + tid) * 4);
;                     const int g = (uu & 63) >> 3; float* sp = ssq_out + (size_t)(NTOKP + rt * 16 + tid) * 16; sp[g] = t; sp[8 + g] = 0.f; }
;                 __syncthreads();
;             }
;         } else {
;             const float sc = rs_from_parts(ssq_in + (size_t)row * 16) * 0.0625f;
;             u32x2 wv; wv.x = cvt_pk_bf16(acc[0] * sc, acc[1] * sc); wv.y = cvt_pk_bf16(acc[2] * sc, acc[3] * sc); *(u32x2*)(xb + (size_t)row * D + col0) = wv;
;         }
.LBB0_1000:
	v_lshl_add_u64 v[20:21], v[14:15], 0, s[0:1]
	v_add_co_u32_e32 v56, vcc, 0xa4c0000, v20
	v_lshl_add_u64 v[22:23], v[12:13], 0, s[0:1]
	s_nop 0
	v_addc_co_u32_e32 v57, vcc, 0, v21, vcc
	v_add_co_u32_e32 v58, vcc, 0xa40000, v22
	s_add_u32 s0, s0, 0x200
	s_nop 0
	v_addc_co_u32_e32 v59, vcc, 0, v23, vcc
	global_load_dwordx4 v[20:23], v[56:57], off
	global_load_dwordx4 v[24:27], v[56:57], off offset:64
	global_load_dwordx4 v[28:31], v[56:57], off offset:128
	global_load_dwordx4 v[32:35], v[56:57], off offset:192
	global_load_dwordx4 v[36:39], v[56:57], off offset:256
	global_load_dwordx4 v[40:43], v[58:59], off
	global_load_dwordx4 v[44:47], v[58:59], off offset:64
	global_load_dwordx4 v[48:51], v[58:59], off offset:128
	global_load_dwordx4 v[52:55], v[58:59], off offset:192
	s_addc_u32 s1, s1, 0
	s_cmpk_eq_i32 s0, 0x800
	s_waitcnt vmcnt(3)
	v_mfma_f32_16x16x32_bf16 v[0:3], v[40:43], v[20:23], v[0:3]
	global_load_dwordx4 v[20:23], v[58:59], off offset:256
	s_waitcnt vmcnt(3)
	v_mfma_f32_16x16x32_bf16 v[0:3], v[44:47], v[24:27], v[0:3]
	global_load_dwordx4 v[24:27], v[58:59], off offset:320
	s_waitcnt vmcnt(3)
	v_mfma_f32_16x16x32_bf16 v[0:3], v[48:51], v[28:31], v[0:3]
	global_load_dwordx4 v[28:31], v[56:57], off offset:320
	s_waitcnt vmcnt(3)
	v_mfma_f32_16x16x32_bf16 v[0:3], v[52:55], v[32:35], v[0:3]
	global_load_dwordx4 v[32:35], v[58:59], off offset:384
	global_load_dwordx4 v[40:43], v[56:57], off offset:384
	s_waitcnt vmcnt(4)
	v_mfma_f32_16x16x32_bf16 v[0:3], v[20:23], v[36:39], v[0:3]
	global_load_dwordx4 v[20:23], v[58:59], off offset:448
	s_waitcnt vmcnt(3)
	v_mfma_f32_16x16x32_bf16 v[0:3], v[24:27], v[28:31], v[0:3]
	global_load_dwordx4 v[24:27], v[56:57], off offset:448
	s_waitcnt vmcnt(2)
	v_mfma_f32_16x16x32_bf16 v[0:3], v[32:35], v[40:43], v[0:3]
	s_waitcnt vmcnt(0)
	v_mfma_f32_16x16x32_bf16 v[0:3], v[20:23], v[24:27], v[0:3]
	s_cbranch_scc0 .LBB0_1000
.Lsgx1_done:
	v_lshlrev_b64 v[10:11], 6, v[10:11]
	v_lshl_add_u64 v[14:15], s[4:5], 0, v[10:11]
	global_load_dwordx4 v[10:13], v[14:15], off
	global_load_dwordx4 v[20:23], v[14:15], off offset:16
	global_load_dwordx4 v[24:27], v[14:15], off offset:32
	global_load_dwordx4 v[28:31], v[14:15], off offset:48
	s_lshl_b32 s0, s3, 4
	s_and_b32 s0, s0, 0x3f0
	v_lshl_add_u64 v[8:9], s[10:11], 0, v[8:9]
	s_add_i32 s3, s3, s6
	s_add_i32 s7, s7, s12
	s_cmpk_gt_i32 s3, 0x7ff
	s_waitcnt vmcnt(3)
	v_mov_b32_e32 v14, v11
	v_mov_b32_e32 v15, v12
	v_mov_b32_e32 v11, v13
	s_waitcnt vmcnt(2)
	v_mov_b32_e32 v12, v21
	v_mov_b32_e32 v13, v22
	v_mov_b32_e32 v21, v23
	v_pk_add_f32 v[10:11], v[14:15], v[10:11]
	v_pk_add_f32 v[12:13], v[12:13], v[20:21]
	v_pk_add_f32 v[10:11], v[10:11], v[10:11] op_sel:[0,1] op_sel_hi:[1,0]
	v_pk_add_f32 v[12:13], v[12:13], v[12:13] op_sel:[0,1] op_sel_hi:[1,0]
	s_waitcnt vmcnt(1)
	v_add_f32_e32 v22, v24, v25
	v_add_f32_e32 v24, v26, v27
	s_waitcnt vmcnt(0)
	v_mov_b32_e32 v23, v30
	v_mov_b32_e32 v25, v31
	v_mov_b32_e32 v11, v28
	v_mov_b32_e32 v13, v29
	v_pk_add_f32 v[14:15], v[22:23], v[24:25]
	v_pk_add_f32 v[10:11], v[10:11], v[12:13]
	s_nop 0
	v_pk_add_f32 v[10:11], v[10:11], v[14:15]
	s_nop 0
	v_add_f32_e32 v4, v10, v11
	v_fmamk_f32 v4, v4, 0x3a800000, v19
	v_mul_f32_e32 v10, 0x4b800000, v4
	v_cmp_gt_f32_e32 vcc, s13, v4
	s_nop 1
	v_cndmask_b32_e32 v4, v4, v10, vcc
	v_rsq_f32_e32 v10, v4
	v_or_b32_e32 v4, s0, v17
	v_lshlrev_b32_e32 v4, 1, v4
	v_lshl_add_u64 v[8:9], v[8:9], 0, v[4:5]
	v_mul_f32_e32 v4, 0x45800000, v10
	v_cndmask_b32_e32 v4, v10, v4, vcc
	v_mul_f32_e32 v4, 0x3d800000, v4
	v_pk_mul_f32 v[0:1], v[0:1], v[4:5] op_sel_hi:[1,0]
	v_pk_mul_f32 v[2:3], v[2:3], v[4:5] op_sel_hi:[1,0]
	v_cvt_pk_bf16_f32 v0, v0, v1
	v_cvt_pk_bf16_f32 v1, v2, v3
	global_store_dwordx2 v[8:9], v[0:1], off
	s_cbranch_scc0 .LBB0_999

; template <int MODE>
; __device__ __forceinline__ void sgemm_sample(LAS unsigned char* lds, const bf16_t* A, const bf16_t* Bt, int K, const float* resid, float* out, bf16_t* xb, float* ssq_out, const float* ssq_in) {
;     ...
;     for (int uu = u; uu < 2048; uu += gridDim.x * 8) {
;         const int rt = uu >> 6, ct = uu & 63; const int row = NTOKP + rt * 16 + fr, col0 = ct * 16 + fq * 4;
;         const bf16_t* ap = A + (size_t)row * K + fq * 8; const bf16_t* bp = Bt + (size_t)(ct * 16 + fr) * K + fq * 8;
;         f32x4 acc = {0.f, 0.f, 0.f, 0.f};
; #pragma unroll 8
;         for (int ks = 0; ks < K / 32; ++ks) {
;             const bf16x8 a = *(const bf16x8*)(ap + ks * 32); const bf16x8 b = *(const bf16x8*)(bp + ks * 32);
;             acc = __builtin_amdgcn_mfma_f32_16x16x32_bf16(b, a, acc, 0, 0, 0);
;         }
.LBB0_1168:
	s_and_b32 s6, s15, 63
	v_lshl_or_b32 v4, s6, 15, v21
	s_ashr_i32 s6, s3, 2
	s_and_b32 s6, s6, -16
	s_add_i32 s6, s6, 0x8000
	v_or_b32_e32 v12, s6, v17
	v_ashrrev_i32_e32 v13, 31, v12
	v_lshlrev_b64 v[8:9], 11, v[12:13]
	v_lshl_add_u64 v[10:11], v[6:7], 0, v[4:5]
	v_lshl_add_u64 v[14:15], v[6:7], 0, v[8:9]
	s_mov_b64 s[18:19], 0
	v_mov_b32_e32 v0, 0
	v_mov_b32_e32 v1, v5
	v_mov_b32_e32 v2, v5
	v_mov_b32_e32 v3, v5
	s_cmpk_lg_i32 s34, 0x100
	s_cbranch_scc1 .LBB0_1169
	s_waitcnt vmcnt(0)
	s_lshr_b32 s100, s2, 3
	s_lshl_b32 s100, s100, 4
	s_add_i32 s100, s100, 0x8000
	s_mul_i32 s100, s100, 0x800
	s_add_u32 s96, s92, s100
	s_addc_u32 s97, s93, 0
	s_add_u32 s96, s96, 0x15780000
	s_addc_u32 s97, s97, 0
	s_and_b32 s100, s2, 7
	s_lshl_b32 s100, s100, 7
	s_mul_i32 s100, s100, 0x800
	s_add_u32 s98, s92, s100
	s_addc_u32 s99, s93, 0
	s_add_u32 s98, s98, 0x1040000
	s_addc_u32 s99, s99, 0
	v_lshrrev_b32_e32 v172, 4, v200
	v_and_b32_e32 v173, 15, v200
	v_and_b32_e32 v174, 15, v172
	v_xor_b32_e32 v173, v173, v174
	v_lshlrev_b32_e32 v173, 4, v173
	s_mov_b32 s100, 0x800
	v_mad_u32_u24 v124, v172, s100, v173
	v_add_u32_e32 v125, 0x10000, v124
	v_add_u32_e32 v126, 0x20000, v124
	v_add_u32_e32 v127, 0x30000, v124
	v_mad_u32_u24 v128, v174, s100, v173
	v_lshlrev_b32_e32 v129, 4, v200
	v_add_u32_e32 v129, 1024, v129
	v_and_b32_e32 v130, 0xff, v200
	v_lshlrev_b32_e32 v130, 4, v130
	v_add_u32_e32 v130, 33792, v130
	v_and_b32_e32 v172, 15, v200
	v_bfe_u32 v173, v200, 4, 2
	v_and_b32_e32 v174, 3, v172
	v_xor_b32_e32 v173, v173, v174
	v_lshlrev_b32_e32 v173, 4, v173
	v_lshrrev_b32_e32 v174, 2, v172
	v_lshl_add_u32 v173, v174, 6, v173
	v_lshl_add_u32 v173, v172, 8, v173
	v_add_u32_e32 v131, 33792, v173
	v_lshrrev_b32_e32 v174, 6, v200
	v_lshlrev_b32_e32 v174, 12, v174
	v_add_u32_e32 v135, v173, v174
	v_add_u32_e32 v135, 1024, v135
	v_xor_b32_e32 v132, 0x40, v131
	v_xor_b32_e32 v136, 0x40, v135
	v_xor_b32_e32 v133, 0x80, v131
	v_xor_b32_e32 v137, 0x80, v135
	v_xor_b32_e32 v134, 0xc0, v131
	v_xor_b32_e32 v138, 0xc0, v135
	global_load_dwordx4 v[64:67], v124, s[98:99]
	global_load_dwordx4 v[68:71], v125, s[98:99]
	global_load_dwordx4 v[72:75], v126, s[98:99]
	global_load_dwordx4 v[76:79], v127, s[98:99]
	global_load_dwordx4 v[80:83], v128, s[96:97]
	s_add_u32 s98, s98, 0x100
	s_addc_u32 s99, s99, 0
	s_add_u32 s96, s96, 0x100
	s_addc_u32 s97, s97, 0
	global_load_dwordx4 v[84:87], v124, s[98:99]
	global_load_dwordx4 v[88:91], v125, s[98:99]
	global_load_dwordx4 v[92:95], v126, s[98:99]
	global_load_dwordx4 v[96:99], v127, s[98:99]
	global_load_dwordx4 v[100:103], v128, s[96:97]
	s_add_u32 s98, s98, 0x100
	s_addc_u32 s99, s99, 0
	s_add_u32 s96, s96, 0x100
	s_addc_u32 s97, s97, 0
	global_load_dwordx4 v[104:107], v124, s[98:99]
	global_load_dwordx4 v[108:111], v125, s[98:99]
	global_load_dwordx4 v[112:115], v126, s[98:99]
	global_load_dwordx4 v[116:119], v127, s[98:99]
	global_load_dwordx4 v[120:123], v128, s[96:97]
	s_add_u32 s98, s98, 0x100
	s_addc_u32 s99, s99, 0
	s_add_u32 s96, s96, 0x100
	s_addc_u32 s97, s97, 0
	s_waitcnt vmcnt(14)
	ds_write_b128 v129, v[64:67]
	s_waitcnt vmcnt(13)
	ds_write_b128 v129, v[68:71] offset:8192
	s_waitcnt vmcnt(12)
	ds_write_b128 v129, v[72:75] offset:16384
	s_waitcnt vmcnt(11)
	ds_write_b128 v129, v[76:79] offset:24576
	s_waitcnt vmcnt(10)
	ds_write_b128 v130, v[80:83]
	s_waitcnt lgkmcnt(0)
	s_barrier
	s_waitcnt vmcnt(9)
	ds_write_b128 v129, v[84:87] offset:36864
	s_waitcnt vmcnt(8)
	ds_write_b128 v129, v[88:91] offset:45056
	s_waitcnt vmcnt(7)
	ds_write_b128 v129, v[92:95] offset:53248
	s_waitcnt vmcnt(6)
	ds_write_b128 v129, v[96:99] offset:61440
	s_waitcnt vmcnt(5)
	ds_write_b128 v130, v[100:103] offset:36864
	global_load_dwordx4 v[64:67], v124, s[98:99]
	global_load_dwordx4 v[68:71], v125, s[98:99]
	global_load_dwordx4 v[72:75], v126, s[98:99]
	global_load_dwordx4 v[76:79], v127, s[98:99]
	global_load_dwordx4 v[80:83], v128, s[96:97]
	s_add_u32 s98, s98, 0x100
	s_addc_u32 s99, s99, 0
	s_add_u32 s96, s96, 0x100
	s_addc_u32 s97, s97, 0
	ds_read_b128 v[140:143], v135
	ds_read_b128 v[144:147], v131
	ds_read_b128 v[148:151], v136
	ds_read_b128 v[152:155], v132
	ds_read_b128 v[156:159], v137
	ds_read_b128 v[160:163], v133
	ds_read_b128 v[164:167], v138
	ds_read_b128 v[168:171], v134
	s_waitcnt lgkmcnt(6)
	v_mfma_f32_16x16x32_bf16 v[0:3], v[140:143], v[144:147], v[0:3]
	s_waitcnt lgkmcnt(4)
	v_mfma_f32_16x16x32_bf16 v[0:3], v[148:151], v[152:155], v[0:3]
	s_waitcnt lgkmcnt(2)
	v_mfma_f32_16x16x32_bf16 v[0:3], v[156:159], v[160:163], v[0:3]
	s_waitcnt lgkmcnt(0)
	v_mfma_f32_16x16x32_bf16 v[0:3], v[164:167], v[168:171], v[0:3]
	s_waitcnt lgkmcnt(0)
	s_barrier
	s_waitcnt vmcnt(9)
	ds_write_b128 v129, v[104:107]
	s_waitcnt vmcnt(8)
	ds_write_b128 v129, v[108:111] offset:8192
	s_waitcnt vmcnt(7)
	ds_write_b128 v129, v[112:115] offset:16384
	s_waitcnt vmcnt(6)
	ds_write_b128 v129, v[116:119] offset:24576
	s_waitcnt vmcnt(5)
	ds_write_b128 v130, v[120:123]
	global_load_dwordx4 v[84:87], v124, s[98:99]
	global_load_dwordx4 v[88:91], v125, s[98:99]
	global_load_dwordx4 v[92:95], v126, s[98:99]
	global_load_dwordx4 v[96:99], v127, s[98:99]
	global_load_dwordx4 v[100:103], v128, s[96:97]
	s_add_u32 s98, s98, 0x100
	s_addc_u32 s99, s99, 0
	s_add_u32 s96, s96, 0x100
	s_addc_u32 s97, s97, 0
	ds_read_b128 v[140:143], v135 offset:36864
	ds_read_b128 v[144:147], v131 offset:36864
	ds_read_b128 v[148:151], v136 offset:36864
	ds_read_b128 v[152:155], v132 offset:36864
	ds_read_b128 v[156:159], v137 offset:36864
	ds_read_b128 v[160:163], v133 offset:36864
	ds_read_b128 v[164:167], v138 offset:36864
	ds_read_b128 v[168:171], v134 offset:36864
	s_waitcnt lgkmcnt(6)
	v_mfma_f32_16x16x32_bf16 v[0:3], v[140:143], v[144:147], v[0:3]
	s_waitcnt lgkmcnt(4)
	v_mfma_f32_16x16x32_bf16 v[0:3], v[148:151], v[152:155], v[0:3]
	s_waitcnt lgkmcnt(2)
	v_mfma_f32_16x16x32_bf16 v[0:3], v[156:159], v[160:163], v[0:3]
	s_waitcnt lgkmcnt(0)
	v_mfma_f32_16x16x32_bf16 v[0:3], v[164:167], v[168:171], v[0:3]
	s_waitcnt lgkmcnt(0)
	s_barrier
; template <int MODE>
; __device__ __forceinline__ void sgemm_sample(LAS unsigned char* lds, const bf16_t* A, const bf16_t* Bt, int K, const float* resid, float* out, bf16_t* xb, float* ssq_out, const float* ssq_in) {
;     ...
; #pragma unroll 8
;         for (int ks = 0; ks < K / 32; ++ks) {
;             const bf16x8 a = *(const bf16x8*)(ap + ks * 32); const bf16x8 b = *(const bf16x8*)(bp + ks * 32);
;             acc = __builtin_amdgcn_mfma_f32_16x16x32_bf16(b, a, acc, 0, 0, 0);
;         }
	s_waitcnt vmcnt(9)
	ds_write_b128 v129, v[64:67] offset:36864
	s_waitcnt vmcnt(8)
	ds_write_b128 v129, v[68:71] offset:45056
	s_waitcnt vmcnt(7)
	ds_write_b128 v129, v[72:75] offset:53248
	s_waitcnt vmcnt(6)
	ds_write_b128 v129, v[76:79] offset:61440
	s_waitcnt vmcnt(5)
	ds_write_b128 v130, v[80:83] offset:36864
	global_load_dwordx4 v[104:107], v124, s[98:99]
	global_load_dwordx4 v[108:111], v125, s[98:99]
	global_load_dwordx4 v[112:115], v126, s[98:99]
	global_load_dwordx4 v[116:119], v127, s[98:99]
	global_load_dwordx4 v[120:123], v128, s[96:97]
	s_add_u32 s98, s98, 0x100
	s_addc_u32 s99, s99, 0
	s_add_u32 s96, s96, 0x100
	s_addc_u32 s97, s97, 0
	ds_read_b128 v[140:143], v135
	ds_read_b128 v[144:147], v131
	ds_read_b128 v[148:151], v136
	ds_read_b128 v[152:155], v132
	ds_read_b128 v[156:159], v137
	ds_read_b128 v[160:163], v133
	ds_read_b128 v[164:167], v138
	ds_read_b128 v[168:171], v134
	s_waitcnt lgkmcnt(6)
	v_mfma_f32_16x16x32_bf16 v[0:3], v[140:143], v[144:147], v[0:3]
	s_waitcnt lgkmcnt(4)
	v_mfma_f32_16x16x32_bf16 v[0:3], v[148:151], v[152:155], v[0:3]
	s_waitcnt lgkmcnt(2)
	v_mfma_f32_16x16x32_bf16 v[0:3], v[156:159], v[160:163], v[0:3]
	s_waitcnt lgkmcnt(0)
	v_mfma_f32_16x16x32_bf16 v[0:3], v[164:167], v[168:171], v[0:3]
	s_waitcnt lgkmcnt(0)
	s_barrier
	s_waitcnt vmcnt(9)
	ds_write_b128 v129, v[84:87]
	s_waitcnt vmcnt(8)
	ds_write_b128 v129, v[88:91] offset:8192
	s_waitcnt vmcnt(7)
	ds_write_b128 v129, v[92:95] offset:16384
	s_waitcnt vmcnt(6)
	ds_write_b128 v129, v[96:99] offset:24576
	s_waitcnt vmcnt(5)
	ds_write_b128 v130, v[100:103]
	global_load_dwordx4 v[64:67], v124, s[98:99]
	global_load_dwordx4 v[68:71], v125, s[98:99]
	global_load_dwordx4 v[72:75], v126, s[98:99]
	global_load_dwordx4 v[76:79], v127, s[98:99]
	global_load_dwordx4 v[80:83], v128, s[96:97]
	s_add_u32 s98, s98, 0x100
	s_addc_u32 s99, s99, 0
	s_add_u32 s96, s96, 0x100
	s_addc_u32 s97, s97, 0
	ds_read_b128 v[140:143], v135 offset:36864
	ds_read_b128 v[144:147], v131 offset:36864
	ds_read_b128 v[148:151], v136 offset:36864
	ds_read_b128 v[152:155], v132 offset:36864
	ds_read_b128 v[156:159], v137 offset:36864
	ds_read_b128 v[160:163], v133 offset:36864
	ds_read_b128 v[164:167], v138 offset:36864
	ds_read_b128 v[168:171], v134 offset:36864
	s_waitcnt lgkmcnt(6)
	v_mfma_f32_16x16x32_bf16 v[0:3], v[140:143], v[144:147], v[0:3]
	s_waitcnt lgkmcnt(4)
	v_mfma_f32_16x16x32_bf16 v[0:3], v[148:151], v[152:155], v[0:3]
	s_waitcnt lgkmcnt(2)
	v_mfma_f32_16x16x32_bf16 v[0:3], v[156:159], v[160:163], v[0:3]
	s_waitcnt lgkmcnt(0)
	v_mfma_f32_16x16x32_bf16 v[0:3], v[164:167], v[168:171], v[0:3]
	s_waitcnt lgkmcnt(0)
	s_barrier
	s_waitcnt vmcnt(9)
	ds_write_b128 v129, v[104:107] offset:36864
	s_waitcnt vmcnt(8)
	ds_write_b128 v129, v[108:111] offset:45056
	s_waitcnt vmcnt(7)
	ds_write_b128 v129, v[112:115] offset:53248
	s_waitcnt vmcnt(6)
	ds_write_b128 v129, v[116:119] offset:61440
	s_waitcnt vmcnt(5)
	ds_write_b128 v130, v[120:123] offset:36864
	global_load_dwordx4 v[84:87], v124, s[98:99]
	global_load_dwordx4 v[88:91], v125, s[98:99]
	global_load_dwordx4 v[92:95], v126, s[98:99]
	global_load_dwordx4 v[96:99], v127, s[98:99]
	global_load_dwordx4 v[100:103], v128, s[96:97]
	s_add_u32 s98, s98, 0x100
	s_addc_u32 s99, s99, 0
	s_add_u32 s96, s96, 0x100
	s_addc_u32 s97, s97, 0
	ds_read_b128 v[140:143], v135
	ds_read_b128 v[144:147], v131
	ds_read_b128 v[148:151], v136
	ds_read_b128 v[152:155], v132
	ds_read_b128 v[156:159], v137
	ds_read_b128 v[160:163], v133
	ds_read_b128 v[164:167], v138
	ds_read_b128 v[168:171], v134
	s_waitcnt lgkmcnt(6)
	v_mfma_f32_16x16x32_bf16 v[0:3], v[140:143], v[144:147], v[0:3]
	s_waitcnt lgkmcnt(4)
	v_mfma_f32_16x16x32_bf16 v[0:3], v[148:151], v[152:155], v[0:3]
	s_waitcnt lgkmcnt(2)
	v_mfma_f32_16x16x32_bf16 v[0:3], v[156:159], v[160:163], v[0:3]
	s_waitcnt lgkmcnt(0)
	v_mfma_f32_16x16x32_bf16 v[0:3], v[164:167], v[168:171], v[0:3]
	s_waitcnt lgkmcnt(0)
	s_barrier
	s_waitcnt vmcnt(9)
	ds_write_b128 v129, v[64:67]
	s_waitcnt vmcnt(8)
	ds_write_b128 v129, v[68:71] offset:8192
	s_waitcnt vmcnt(7)
	ds_write_b128 v129, v[72:75] offset:16384
	s_waitcnt vmcnt(6)
	ds_write_b128 v129, v[76:79] offset:24576
	s_waitcnt vmcnt(5)
	ds_write_b128 v130, v[80:83]
	ds_read_b128 v[140:143], v135 offset:36864
	ds_read_b128 v[144:147], v131 offset:36864
	ds_read_b128 v[148:151], v136 offset:36864
	ds_read_b128 v[152:155], v132 offset:36864
	ds_read_b128 v[156:159], v137 offset:36864
	ds_read_b128 v[160:163], v133 offset:36864
	ds_read_b128 v[164:167], v138 offset:36864
	ds_read_b128 v[168:171], v134 offset:36864
	s_waitcnt lgkmcnt(6)
	v_mfma_f32_16x16x32_bf16 v[0:3], v[140:143], v[144:147], v[0:3]
	s_waitcnt lgkmcnt(4)
	v_mfma_f32_16x16x32_bf16 v[0:3], v[148:151], v[152:155], v[0:3]
	s_waitcnt lgkmcnt(2)
	v_mfma_f32_16x16x32_bf16 v[0:3], v[156:159], v[160:163], v[0:3]
	s_waitcnt lgkmcnt(0)
	v_mfma_f32_16x16x32_bf16 v[0:3], v[164:167], v[168:171], v[0:3]
	s_waitcnt lgkmcnt(0)
	s_barrier
	s_waitcnt vmcnt(4)
	ds_write_b128 v129, v[84:87] offset:36864
	s_waitcnt vmcnt(3)
	ds_write_b128 v129, v[88:91] offset:45056
	s_waitcnt vmcnt(2)
	ds_write_b128 v129, v[92:95] offset:53248
	s_waitcnt vmcnt(1)
	ds_write_b128 v129, v[96:99] offset:61440
	s_waitcnt vmcnt(0)
	ds_write_b128 v130, v[100:103] offset:36864
	ds_read_b128 v[140:143], v135
	ds_read_b128 v[144:147], v131
	ds_read_b128 v[148:151], v136
	ds_read_b128 v[152:155], v132
	ds_read_b128 v[156:159], v137
	ds_read_b128 v[160:163], v133
	ds_read_b128 v[164:167], v138
	ds_read_b128 v[168:171], v134
	s_waitcnt lgkmcnt(6)
	v_mfma_f32_16x16x32_bf16 v[0:3], v[140:143], v[144:147], v[0:3]
	s_waitcnt lgkmcnt(4)
	v_mfma_f32_16x16x32_bf16 v[0:3], v[148:151], v[152:155], v[0:3]
	s_waitcnt lgkmcnt(2)
	v_mfma_f32_16x16x32_bf16 v[0:3], v[156:159], v[160:163], v[0:3]
	s_waitcnt lgkmcnt(0)
	v_mfma_f32_16x16x32_bf16 v[0:3], v[164:167], v[168:171], v[0:3]
	s_waitcnt lgkmcnt(0)
	s_barrier
	ds_read_b128 v[140:143], v135 offset:36864
	ds_read_b128 v[144:147], v131 offset:36864
	ds_read_b128 v[148:151], v136 offset:36864
	ds_read_b128 v[152:155], v132 offset:36864
	ds_read_b128 v[156:159], v137 offset:36864
	ds_read_b128 v[160:163], v133 offset:36864
	ds_read_b128 v[164:167], v138 offset:36864
	ds_read_b128 v[168:171], v134 offset:36864
	s_waitcnt lgkmcnt(6)
	v_mfma_f32_16x16x32_bf16 v[0:3], v[140:143], v[144:147], v[0:3]
	s_waitcnt lgkmcnt(4)
	v_mfma_f32_16x16x32_bf16 v[0:3], v[148:151], v[152:155], v[0:3]
	s_waitcnt lgkmcnt(2)
	v_mfma_f32_16x16x32_bf16 v[0:3], v[156:159], v[160:163], v[0:3]
	s_waitcnt lgkmcnt(0)
	v_mfma_f32_16x16x32_bf16 v[0:3], v[164:167], v[168:171], v[0:3]
	s_nop 7
	s_branch .Lsgx2_done
; #define LAS __attribute__((address_space(3)))
; __device__ __forceinline__ unsigned cvt_pk_bf16(float lo, float hi) { f32x2 f = {lo, hi}; bf16x2_t v = __builtin_convertvector(f, bf16x2_t); return __builtin_bit_cast(unsigned, v); }
; template <int MODE>
; __device__ __forceinline__ void sgemm_sample(LAS unsigned char* lds, const bf16_t* A, const bf16_t* Bt, int K, const float* resid, float* out, bf16_t* xb, float* ssq_out, const float* ssq_in) {
;     ...
; #pragma unroll 8
;         for (int ks = 0; ks < K / 32; ++ks) {
;             const bf16x8 a = *(const bf16x8*)(ap + ks * 32); const bf16x8 b = *(const bf16x8*)(bp + ks * 32);
;             acc = __builtin_amdgcn_mfma_f32_16x16x32_bf16(b, a, acc, 0, 0, 0);
;         }
;         if (MODE == 0) {
;             const f32x4 x = *(const f32x4*)(resid + (size_t)(row - NTOKP) * D + col0) + acc;
;             *(f32x4*)(out + (size_t)row * D + col0) = x;
;             if (xb) { u32x2 wv; wv.x = cvt_pk_bf16(x[0], x[1]); wv.y = cvt_pk_bf16(x[2], x[3]); *(u32x2*)(xb + (size_t)row * D + col0) = wv; }
;             if (ssq_out) {
;                 float ss = (x[0] * x[0] + x[1] * x[1]) + (x[2] * x[2] + x[3] * x[3]); ss += __shfl_xor(ss, 16); ss += __shfl_xor(ss, 32);
;                 if (fq == 0) *(LAS float*)(lds + (w * 16 + fr) * 4) = ss;
;                 __syncthreads();
;                 if (tid < 16) { float t = 0.f;
; #pragma unroll
;                     for (int i = 0; i < 8; ++i) t += *(const LAS float*)(lds + (i * 16 + tid) * 4);
;                     const int g = (uu & 63) >> 3; float* sp = ssq_out + (size_t)(NTOKP + rt * 16 + tid) * 16; sp[g] = t; sp[8 + g] = 0.f; }
;                 __syncthreads();
;             }
.LBB0_1169:
	v_lshl_add_u64 v[24:25], v[14:15], 0, s[18:19]
	v_add_co_u32_e32 v60, vcc, 0x15780000, v24
	v_lshl_add_u64 v[26:27], v[10:11], 0, s[18:19]
	s_nop 0
	v_addc_co_u32_e32 v61, vcc, 0, v25, vcc
	v_add_co_u32_e32 v62, vcc, 0x1040000, v26
	s_add_u32 s18, s18, 0x200
	s_nop 0
	v_addc_co_u32_e32 v63, vcc, 0, v27, vcc
	global_load_dwordx4 v[24:27], v[60:61], off
	global_load_dwordx4 v[28:31], v[60:61], off offset:64
	global_load_dwordx4 v[32:35], v[60:61], off offset:128
	global_load_dwordx4 v[36:39], v[60:61], off offset:192
	global_load_dwordx4 v[40:43], v[60:61], off offset:256
	global_load_dwordx4 v[44:47], v[62:63], off
	global_load_dwordx4 v[48:51], v[62:63], off offset:64
	global_load_dwordx4 v[52:55], v[62:63], off offset:128
	global_load_dwordx4 v[56:59], v[62:63], off offset:192
	s_addc_u32 s19, s19, 0
	s_cmpk_eq_i32 s18, 0x800
	s_waitcnt vmcnt(3)
	v_mfma_f32_16x16x32_bf16 v[0:3], v[44:47], v[24:27], v[0:3]
	global_load_dwordx4 v[24:27], v[62:63], off offset:256
	s_waitcnt vmcnt(3)
	v_mfma_f32_16x16x32_bf16 v[0:3], v[48:51], v[28:31], v[0:3]
	global_load_dwordx4 v[28:31], v[62:63], off offset:320
	s_waitcnt vmcnt(3)
	v_mfma_f32_16x16x32_bf16 v[0:3], v[52:55], v[32:35], v[0:3]
	global_load_dwordx4 v[32:35], v[60:61], off offset:320
	s_waitcnt vmcnt(3)
	v_mfma_f32_16x16x32_bf16 v[0:3], v[56:59], v[36:39], v[0:3]
	global_load_dwordx4 v[36:39], v[62:63], off offset:384
	global_load_dwordx4 v[44:47], v[60:61], off offset:384
	s_waitcnt vmcnt(4)
	v_mfma_f32_16x16x32_bf16 v[0:3], v[24:27], v[40:43], v[0:3]
	global_load_dwordx4 v[24:27], v[62:63], off offset:448
	s_waitcnt vmcnt(3)
	v_mfma_f32_16x16x32_bf16 v[0:3], v[28:31], v[32:35], v[0:3]
	global_load_dwordx4 v[28:31], v[60:61], off offset:448
	s_waitcnt vmcnt(2)
	v_mfma_f32_16x16x32_bf16 v[0:3], v[36:39], v[44:47], v[0:3]
	s_waitcnt vmcnt(0)
	v_mfma_f32_16x16x32_bf16 v[0:3], v[24:27], v[28:31], v[0:3]
	s_cbranch_scc0 .LBB0_1169
.Lsgx2_done:
	s_and_b32 s20, s3, 63
	v_lshl_or_b32 v24, s20, 4, v18
	v_lshlrev_b64 v[14:15], 12, v[12:13]
	v_lshl_add_u64 v[10:11], s[10:11], 0, v[14:15]
	v_lshlrev_b32_e32 v4, 2, v24
	v_lshl_add_u64 v[10:11], v[10:11], 0, v[4:5]
	v_add_co_u32_e32 v10, vcc, 0xf8000000, v10
	v_lshl_add_u64 v[14:15], s[90:91], 0, v[14:15]
	s_nop 0
	v_addc_co_u32_e32 v11, vcc, -1, v11, vcc
	global_load_dwordx4 v[10:13], v[10:11], off
	s_waitcnt vmcnt(0)
	v_pk_add_f32 v[2:3], v[2:3], v[12:13]
	v_pk_add_f32 v[0:1], v[0:1], v[10:11]
	v_mul_f32_e32 v11, v3, v3
	v_mul_f32_e32 v10, v1, v1
	v_fmac_f32_e32 v10, v0, v0
	v_fmac_f32_e32 v11, v2, v2
	v_add_f32_e32 v12, v10, v11
	ds_bpermute_b32 v13, v19, v12
	v_lshl_add_u64 v[10:11], v[14:15], 0, v[4:5]
	global_store_dwordx4 v[10:11], v[0:3], off
	v_cvt_pk_bf16_f32 v10, v0, v1
	v_cvt_pk_bf16_f32 v11, v2, v3
	s_waitcnt lgkmcnt(0)
	v_add_f32_e32 v0, v12, v13
	ds_bpermute_b32 v1, v20, v0
	v_lshl_add_u64 v[2:3], s[12:13], 0, v[8:9]
	v_lshlrev_b32_e32 v4, 1, v24
	v_lshl_add_u64 v[2:3], v[2:3], 0, v[4:5]
	global_store_dwordx2 v[2:3], v[10:11], off
	s_and_saveexec_b64 s[18:19], s[0:1]
	s_cbranch_execz .LBB0_1172
	s_waitcnt lgkmcnt(0)
	v_add_f32_e32 v0, v0, v1
	ds_write_b32 v22, v0

; template <int MODE>
; __device__ __forceinline__ void sgemm_sample(LAS unsigned char* lds, const bf16_t* A, const bf16_t* Bt, int K, const float* resid, float* out, bf16_t* xb, float* ssq_out, const float* ssq_in) {
;     ...
;     for (int uu = u; uu < 2048; uu += gridDim.x * 8) {
;         const int rt = uu >> 6, ct = uu & 63; const int row = NTOKP + rt * 16 + fr, col0 = ct * 16 + fq * 4;
;         const bf16_t* ap = A + (size_t)row * K + fq * 8; const bf16_t* bp = Bt + (size_t)(ct * 16 + fr) * K + fq * 8;
;         f32x4 acc = {0.f, 0.f, 0.f, 0.f};
; #pragma unroll 8
;         for (int ks = 0; ks < K / 32; ++ks) {
;             const bf16x8 a = *(const bf16x8*)(ap + ks * 32); const bf16x8 b = *(const bf16x8*)(bp + ks * 32);
;             acc = __builtin_amdgcn_mfma_f32_16x16x32_bf16(b, a, acc, 0, 0, 0);
;         }
.LBB0_1348:
	s_ashr_i32 s0, s3, 2
	s_and_b32 s0, s0, -16
	v_add_u32_e32 v8, s0, v16
	s_lshl_b32 s0, s3, 4
	s_and_b32 s10, s0, 0x3f0
	v_or_b32_e32 v0, s10, v14
	v_mul_u32_u24_e32 v0, 0xb00, v0
	v_mad_i64_i32 v[10:11], s[0:1], v8, s5, v[6:7]
	v_lshlrev_b32_e32 v4, 1, v0
	v_ashrrev_i32_e32 v9, 31, v8
	v_lshl_add_u64 v[12:13], v[6:7], 0, v[4:5]
	s_mov_b64 s[0:1], 0
	v_mov_b32_e32 v0, 0
	s_waitcnt lgkmcnt(0)
	v_mov_b32_e32 v1, v5
	v_mov_b32_e32 v2, v5
	v_mov_b32_e32 v3, v5
	s_cmpk_lg_i32 s34, 0x100
	s_cbranch_scc1 .LBB0_1349
	s_waitcnt vmcnt(0)
	s_lshr_b32 s100, s2, 3
	s_lshl_b32 s100, s100, 4
	s_add_i32 s100, s100, 0x8000
	s_mul_i32 s100, s100, 0x1600
	s_add_u32 s96, s92, s100
	s_addc_u32 s97, s93, 0
	s_add_u32 s96, s96, 0x22c0000
	s_addc_u32 s97, s97, 0
	s_and_b32 s100, s2, 7
	s_lshl_b32 s100, s100, 7
	s_mul_i32 s100, s100, 0x1600
	s_add_u32 s98, s92, s100
	s_addc_u32 s99, s93, 0
	s_add_u32 s98, s98, 0x1d40000
	s_addc_u32 s99, s99, 0
	v_lshrrev_b32_e32 v172, 4, v200
	v_and_b32_e32 v173, 15, v200
	v_and_b32_e32 v174, 15, v172
	v_xor_b32_e32 v173, v173, v174
	v_lshlrev_b32_e32 v173, 4, v173
	s_mov_b32 s100, 0x1600
	v_mad_u32_u24 v124, v172, s100, v173
	v_add_u32_e32 v125, 0x2c000, v124
	v_add_u32_e32 v126, 0x58000, v124
	v_add_u32_e32 v127, 0x84000, v124
	v_mad_u32_u24 v128, v174, s100, v173
	v_lshlrev_b32_e32 v129, 4, v200
	v_add_u32_e32 v129, 1024, v129
	v_and_b32_e32 v130, 0xff, v200
	v_lshlrev_b32_e32 v130, 4, v130
	v_add_u32_e32 v130, 33792, v130
	v_and_b32_e32 v172, 15, v200
	v_bfe_u32 v173, v200, 4, 2
	v_and_b32_e32 v174, 3, v172
	v_xor_b32_e32 v173, v173, v174
	v_lshlrev_b32_e32 v173, 4, v173
	v_lshrrev_b32_e32 v174, 2, v172
	v_lshl_add_u32 v173, v174, 6, v173
	v_lshl_add_u32 v173, v172, 8, v173
	v_add_u32_e32 v131, 33792, v173
	v_lshrrev_b32_e32 v174, 6, v200
	v_lshlrev_b32_e32 v174, 12, v174
	v_add_u32_e32 v135, v173, v174
	v_add_u32_e32 v135, 1024, v135
	v_xor_b32_e32 v132, 0x40, v131
	v_xor_b32_e32 v136, 0x40, v135
	v_xor_b32_e32 v133, 0x80, v131
	v_xor_b32_e32 v137, 0x80, v135
	v_xor_b32_e32 v134, 0xc0, v131
	v_xor_b32_e32 v138, 0xc0, v135
	global_load_dwordx4 v[64:67], v124, s[98:99]
	global_load_dwordx4 v[68:71], v125, s[98:99]
	global_load_dwordx4 v[72:75], v126, s[98:99]
	global_load_dwordx4 v[76:79], v127, s[98:99]
	global_load_dwordx4 v[80:83], v128, s[96:97]
	s_add_u32 s98, s98, 0x100
	s_addc_u32 s99, s99, 0
	s_add_u32 s96, s96, 0x100
	s_addc_u32 s97, s97, 0
	global_load_dwordx4 v[84:87], v124, s[98:99]
	global_load_dwordx4 v[88:91], v125, s[98:99]
	global_load_dwordx4 v[92:95], v126, s[98:99]
	global_load_dwordx4 v[96:99], v127, s[98:99]
	global_load_dwordx4 v[100:103], v128, s[96:97]
	s_add_u32 s98, s98, 0x100
	s_addc_u32 s99, s99, 0
	s_add_u32 s96, s96, 0x100
	s_addc_u32 s97, s97, 0
	global_load_dwordx4 v[104:107], v124, s[98:99]
	global_load_dwordx4 v[108:111], v125, s[98:99]
	global_load_dwordx4 v[112:115], v126, s[98:99]
	global_load_dwordx4 v[116:119], v127, s[98:99]
	global_load_dwordx4 v[120:123], v128, s[96:97]
	s_add_u32 s98, s98, 0x100
	s_addc_u32 s99, s99, 0
	s_add_u32 s96, s96, 0x100
	s_addc_u32 s97, s97, 0
	s_waitcnt vmcnt(14)
	ds_write_b128 v129, v[64:67]
	s_waitcnt vmcnt(13)
	ds_write_b128 v129, v[68:71] offset:8192
	s_waitcnt vmcnt(12)
	ds_write_b128 v129, v[72:75] offset:16384
	s_waitcnt vmcnt(11)
	ds_write_b128 v129, v[76:79] offset:24576
	s_waitcnt vmcnt(10)
	ds_write_b128 v130, v[80:83]
	s_waitcnt lgkmcnt(0)
	s_barrier
	s_waitcnt vmcnt(9)
	ds_write_b128 v129, v[84:87] offset:36864
	s_waitcnt vmcnt(8)
	ds_write_b128 v129, v[88:91] offset:45056
	s_waitcnt vmcnt(7)
	ds_write_b128 v129, v[92:95] offset:53248
	s_waitcnt vmcnt(6)
	ds_write_b128 v129, v[96:99] offset:61440
	s_waitcnt vmcnt(5)
	ds_write_b128 v130, v[100:103] offset:36864
	global_load_dwordx4 v[64:67], v124, s[98:99]
	global_load_dwordx4 v[68:71], v125, s[98:99]
	global_load_dwordx4 v[72:75], v126, s[98:99]
	global_load_dwordx4 v[76:79], v127, s[98:99]
	global_load_dwordx4 v[80:83], v128, s[96:97]
	s_add_u32 s98, s98, 0x100
	s_addc_u32 s99, s99, 0
	s_add_u32 s96, s96, 0x100
	s_addc_u32 s97, s97, 0
	ds_read_b128 v[140:143], v135
	ds_read_b128 v[144:147], v131
	ds_read_b128 v[148:151], v136
	ds_read_b128 v[152:155], v132
	ds_read_b128 v[156:159], v137
	ds_read_b128 v[160:163], v133
	ds_read_b128 v[164:167], v138
	ds_read_b128 v[168:171], v134
	s_waitcnt lgkmcnt(6)
	v_mfma_f32_16x16x32_bf16 v[0:3], v[140:143], v[144:147], v[0:3]
	s_waitcnt lgkmcnt(4)
	v_mfma_f32_16x16x32_bf16 v[0:3], v[148:151], v[152:155], v[0:3]
	s_waitcnt lgkmcnt(2)
	v_mfma_f32_16x16x32_bf16 v[0:3], v[156:159], v[160:163], v[0:3]
	s_waitcnt lgkmcnt(0)
	v_mfma_f32_16x16x32_bf16 v[0:3], v[164:167], v[168:171], v[0:3]
	s_waitcnt lgkmcnt(0)
	s_barrier
	s_waitcnt vmcnt(9)
	ds_write_b128 v129, v[104:107]
	s_waitcnt vmcnt(8)
	ds_write_b128 v129, v[108:111] offset:8192
	s_waitcnt vmcnt(7)
	ds_write_b128 v129, v[112:115] offset:16384
	s_waitcnt vmcnt(6)
	ds_write_b128 v129, v[116:119] offset:24576
	s_waitcnt vmcnt(5)
	ds_write_b128 v130, v[120:123]
	global_load_dwordx4 v[84:87], v124, s[98:99]
	global_load_dwordx4 v[88:91], v125, s[98:99]
	global_load_dwordx4 v[92:95], v126, s[98:99]
	global_load_dwordx4 v[96:99], v127, s[98:99]
	global_load_dwordx4 v[100:103], v128, s[96:97]
	s_add_u32 s98, s98, 0x100
	s_addc_u32 s99, s99, 0
	s_add_u32 s96, s96, 0x100
	s_addc_u32 s97, s97, 0
	ds_read_b128 v[140:143], v135 offset:36864
	ds_read_b128 v[144:147], v131 offset:36864
	ds_read_b128 v[148:151], v136 offset:36864
	ds_read_b128 v[152:155], v132 offset:36864
	ds_read_b128 v[156:159], v137 offset:36864
	ds_read_b128 v[160:163], v133 offset:36864
	ds_read_b128 v[164:167], v138 offset:36864
	ds_read_b128 v[168:171], v134 offset:36864
	s_waitcnt lgkmcnt(6)
	v_mfma_f32_16x16x32_bf16 v[0:3], v[140:143], v[144:147], v[0:3]
	s_waitcnt lgkmcnt(4)
	v_mfma_f32_16x16x32_bf16 v[0:3], v[148:151], v[152:155], v[0:3]
	s_waitcnt lgkmcnt(2)
	v_mfma_f32_16x16x32_bf16 v[0:3], v[156:159], v[160:163], v[0:3]
	s_waitcnt lgkmcnt(0)
	v_mfma_f32_16x16x32_bf16 v[0:3], v[164:167], v[168:171], v[0:3]
	s_waitcnt lgkmcnt(0)
	s_barrier
; template <int MODE>
; __device__ __forceinline__ void sgemm_sample(LAS unsigned char* lds, const bf16_t* A, const bf16_t* Bt, int K, const float* resid, float* out, bf16_t* xb, float* ssq_out, const float* ssq_in) {
;     ...
; #pragma unroll 8
;         for (int ks = 0; ks < K / 32; ++ks) {
;             const bf16x8 a = *(const bf16x8*)(ap + ks * 32); const bf16x8 b = *(const bf16x8*)(bp + ks * 32);
;             acc = __builtin_amdgcn_mfma_f32_16x16x32_bf16(b, a, acc, 0, 0, 0);
;         }
	s_waitcnt vmcnt(9)
	ds_write_b128 v129, v[64:67] offset:36864
	s_waitcnt vmcnt(8)
	ds_write_b128 v129, v[68:71] offset:45056
	s_waitcnt vmcnt(7)
	ds_write_b128 v129, v[72:75] offset:53248
	s_waitcnt vmcnt(6)
	ds_write_b128 v129, v[76:79] offset:61440
	s_waitcnt vmcnt(5)
	ds_write_b128 v130, v[80:83] offset:36864
	global_load_dwordx4 v[104:107], v124, s[98:99]
	global_load_dwordx4 v[108:111], v125, s[98:99]
	global_load_dwordx4 v[112:115], v126, s[98:99]
	global_load_dwordx4 v[116:119], v127, s[98:99]
	global_load_dwordx4 v[120:123], v128, s[96:97]
	s_add_u32 s98, s98, 0x100
	s_addc_u32 s99, s99, 0
	s_add_u32 s96, s96, 0x100
	s_addc_u32 s97, s97, 0
	ds_read_b128 v[140:143], v135
	ds_read_b128 v[144:147], v131
	ds_read_b128 v[148:151], v136
	ds_read_b128 v[152:155], v132
	ds_read_b128 v[156:159], v137
	ds_read_b128 v[160:163], v133
	ds_read_b128 v[164:167], v138
	ds_read_b128 v[168:171], v134
	s_waitcnt lgkmcnt(6)
	v_mfma_f32_16x16x32_bf16 v[0:3], v[140:143], v[144:147], v[0:3]
	s_waitcnt lgkmcnt(4)
	v_mfma_f32_16x16x32_bf16 v[0:3], v[148:151], v[152:155], v[0:3]
	s_waitcnt lgkmcnt(2)
	v_mfma_f32_16x16x32_bf16 v[0:3], v[156:159], v[160:163], v[0:3]
	s_waitcnt lgkmcnt(0)
	v_mfma_f32_16x16x32_bf16 v[0:3], v[164:167], v[168:171], v[0:3]
	s_waitcnt lgkmcnt(0)
	s_barrier
	s_waitcnt vmcnt(9)
	ds_write_b128 v129, v[84:87]
	s_waitcnt vmcnt(8)
	ds_write_b128 v129, v[88:91] offset:8192
	s_waitcnt vmcnt(7)
	ds_write_b128 v129, v[92:95] offset:16384
	s_waitcnt vmcnt(6)
	ds_write_b128 v129, v[96:99] offset:24576
	s_waitcnt vmcnt(5)
	ds_write_b128 v130, v[100:103]
	global_load_dwordx4 v[64:67], v124, s[98:99]
	global_load_dwordx4 v[68:71], v125, s[98:99]
	global_load_dwordx4 v[72:75], v126, s[98:99]
	global_load_dwordx4 v[76:79], v127, s[98:99]
	global_load_dwordx4 v[80:83], v128, s[96:97]
	s_add_u32 s98, s98, 0x100
	s_addc_u32 s99, s99, 0
	s_add_u32 s96, s96, 0x100
	s_addc_u32 s97, s97, 0
	ds_read_b128 v[140:143], v135 offset:36864
	ds_read_b128 v[144:147], v131 offset:36864
	ds_read_b128 v[148:151], v136 offset:36864
	ds_read_b128 v[152:155], v132 offset:36864
	ds_read_b128 v[156:159], v137 offset:36864
	ds_read_b128 v[160:163], v133 offset:36864
	ds_read_b128 v[164:167], v138 offset:36864
	ds_read_b128 v[168:171], v134 offset:36864
	s_waitcnt lgkmcnt(6)
	v_mfma_f32_16x16x32_bf16 v[0:3], v[140:143], v[144:147], v[0:3]
	s_waitcnt lgkmcnt(4)
	v_mfma_f32_16x16x32_bf16 v[0:3], v[148:151], v[152:155], v[0:3]
	s_waitcnt lgkmcnt(2)
	v_mfma_f32_16x16x32_bf16 v[0:3], v[156:159], v[160:163], v[0:3]
	s_waitcnt lgkmcnt(0)
	v_mfma_f32_16x16x32_bf16 v[0:3], v[164:167], v[168:171], v[0:3]
	s_waitcnt lgkmcnt(0)
	s_barrier
	s_waitcnt vmcnt(9)
	ds_write_b128 v129, v[104:107] offset:36864
	s_waitcnt vmcnt(8)
	ds_write_b128 v129, v[108:111] offset:45056
	s_waitcnt vmcnt(7)
	ds_write_b128 v129, v[112:115] offset:53248
	s_waitcnt vmcnt(6)
	ds_write_b128 v129, v[116:119] offset:61440
	s_waitcnt vmcnt(5)
	ds_write_b128 v130, v[120:123] offset:36864
	global_load_dwordx4 v[84:87], v124, s[98:99]
	global_load_dwordx4 v[88:91], v125, s[98:99]
	global_load_dwordx4 v[92:95], v126, s[98:99]
	global_load_dwordx4 v[96:99], v127, s[98:99]
	global_load_dwordx4 v[100:103], v128, s[96:97]
	s_add_u32 s98, s98, 0x100
	s_addc_u32 s99, s99, 0
	s_add_u32 s96, s96, 0x100
	s_addc_u32 s97, s97, 0
	ds_read_b128 v[140:143], v135
	ds_read_b128 v[144:147], v131
	ds_read_b128 v[148:151], v136
	ds_read_b128 v[152:155], v132
	ds_read_b128 v[156:159], v137
	ds_read_b128 v[160:163], v133
	ds_read_b128 v[164:167], v138
	ds_read_b128 v[168:171], v134
	s_waitcnt lgkmcnt(6)
	v_mfma_f32_16x16x32_bf16 v[0:3], v[140:143], v[144:147], v[0:3]
	s_waitcnt lgkmcnt(4)
	v_mfma_f32_16x16x32_bf16 v[0:3], v[148:151], v[152:155], v[0:3]
	s_waitcnt lgkmcnt(2)
	v_mfma_f32_16x16x32_bf16 v[0:3], v[156:159], v[160:163], v[0:3]
	s_waitcnt lgkmcnt(0)
	v_mfma_f32_16x16x32_bf16 v[0:3], v[164:167], v[168:171], v[0:3]
	s_waitcnt lgkmcnt(0)
	s_barrier
	s_waitcnt vmcnt(9)
	ds_write_b128 v129, v[64:67]
	s_waitcnt vmcnt(8)
	ds_write_b128 v129, v[68:71] offset:8192
	s_waitcnt vmcnt(7)
	ds_write_b128 v129, v[72:75] offset:16384
	s_waitcnt vmcnt(6)
	ds_write_b128 v129, v[76:79] offset:24576
	s_waitcnt vmcnt(5)
	ds_write_b128 v130, v[80:83]
	global_load_dwordx4 v[104:107], v124, s[98:99]
	global_load_dwordx4 v[108:111], v125, s[98:99]
	global_load_dwordx4 v[112:115], v126, s[98:99]
	global_load_dwordx4 v[116:119], v127, s[98:99]
	global_load_dwordx4 v[120:123], v128, s[96:97]
	s_add_u32 s98, s98, 0x100
	s_addc_u32 s99, s99, 0
	s_add_u32 s96, s96, 0x100
	s_addc_u32 s97, s97, 0
	ds_read_b128 v[140:143], v135 offset:36864
	ds_read_b128 v[144:147], v131 offset:36864
	ds_read_b128 v[148:151], v136 offset:36864
	ds_read_b128 v[152:155], v132 offset:36864
	ds_read_b128 v[156:159], v137 offset:36864
	ds_read_b128 v[160:163], v133 offset:36864
	ds_read_b128 v[164:167], v138 offset:36864
	ds_read_b128 v[168:171], v134 offset:36864
	s_waitcnt lgkmcnt(6)
	v_mfma_f32_16x16x32_bf16 v[0:3], v[140:143], v[144:147], v[0:3]
	s_waitcnt lgkmcnt(4)
	v_mfma_f32_16x16x32_bf16 v[0:3], v[148:151], v[152:155], v[0:3]
	s_waitcnt lgkmcnt(2)
	v_mfma_f32_16x16x32_bf16 v[0:3], v[156:159], v[160:163], v[0:3]
	s_waitcnt lgkmcnt(0)
	v_mfma_f32_16x16x32_bf16 v[0:3], v[164:167], v[168:171], v[0:3]
	s_waitcnt lgkmcnt(0)
	s_barrier
; template <int MODE>
; __device__ __forceinline__ void sgemm_sample(LAS unsigned char* lds, const bf16_t* A, const bf16_t* Bt, int K, const float* resid, float* out, bf16_t* xb, float* ssq_out, const float* ssq_in) {
;     ...
; #pragma unroll 8
;         for (int ks = 0; ks < K / 32; ++ks) {
;             const bf16x8 a = *(const bf16x8*)(ap + ks * 32); const bf16x8 b = *(const bf16x8*)(bp + ks * 32);
;             acc = __builtin_amdgcn_mfma_f32_16x16x32_bf16(b, a, acc, 0, 0, 0);
;         }
	s_waitcnt vmcnt(9)
	ds_write_b128 v129, v[84:87] offset:36864
	s_waitcnt vmcnt(8)
	ds_write_b128 v129, v[88:91] offset:45056
	s_waitcnt vmcnt(7)
	ds_write_b128 v129, v[92:95] offset:53248
	s_waitcnt vmcnt(6)
	ds_write_b128 v129, v[96:99] offset:61440
	s_waitcnt vmcnt(5)
	ds_write_b128 v130, v[100:103] offset:36864
	global_load_dwordx4 v[64:67], v124, s[98:99]
	global_load_dwordx4 v[68:71], v125, s[98:99]
	global_load_dwordx4 v[72:75], v126, s[98:99]
	global_load_dwordx4 v[76:79], v127, s[98:99]
	global_load_dwordx4 v[80:83], v128, s[96:97]
	s_add_u32 s98, s98, 0x100
	s_addc_u32 s99, s99, 0
	s_add_u32 s96, s96, 0x100
	s_addc_u32 s97, s97, 0
	ds_read_b128 v[140:143], v135
	ds_read_b128 v[144:147], v131
	ds_read_b128 v[148:151], v136
	ds_read_b128 v[152:155], v132
	ds_read_b128 v[156:159], v137
	ds_read_b128 v[160:163], v133
	ds_read_b128 v[164:167], v138
	ds_read_b128 v[168:171], v134
	s_waitcnt lgkmcnt(6)
	v_mfma_f32_16x16x32_bf16 v[0:3], v[140:143], v[144:147], v[0:3]
	s_waitcnt lgkmcnt(4)
	v_mfma_f32_16x16x32_bf16 v[0:3], v[148:151], v[152:155], v[0:3]
	s_waitcnt lgkmcnt(2)
	v_mfma_f32_16x16x32_bf16 v[0:3], v[156:159], v[160:163], v[0:3]
	s_waitcnt lgkmcnt(0)
	v_mfma_f32_16x16x32_bf16 v[0:3], v[164:167], v[168:171], v[0:3]
	s_waitcnt lgkmcnt(0)
	s_barrier
	s_waitcnt vmcnt(9)
	ds_write_b128 v129, v[104:107]
	s_waitcnt vmcnt(8)
	ds_write_b128 v129, v[108:111] offset:8192
	s_waitcnt vmcnt(7)
	ds_write_b128 v129, v[112:115] offset:16384
	s_waitcnt vmcnt(6)
	ds_write_b128 v129, v[116:119] offset:24576
	s_waitcnt vmcnt(5)
	ds_write_b128 v130, v[120:123]
	global_load_dwordx4 v[84:87], v124, s[98:99]
	global_load_dwordx4 v[88:91], v125, s[98:99]
	global_load_dwordx4 v[92:95], v126, s[98:99]
	global_load_dwordx4 v[96:99], v127, s[98:99]
	global_load_dwordx4 v[100:103], v128, s[96:97]
	s_add_u32 s98, s98, 0x100
	s_addc_u32 s99, s99, 0
	s_add_u32 s96, s96, 0x100
	s_addc_u32 s97, s97, 0
	ds_read_b128 v[140:143], v135 offset:36864
	ds_read_b128 v[144:147], v131 offset:36864
	ds_read_b128 v[148:151], v136 offset:36864
	ds_read_b128 v[152:155], v132 offset:36864
	ds_read_b128 v[156:159], v137 offset:36864
	ds_read_b128 v[160:163], v133 offset:36864
	ds_read_b128 v[164:167], v138 offset:36864
	ds_read_b128 v[168:171], v134 offset:36864
	s_waitcnt lgkmcnt(6)
	v_mfma_f32_16x16x32_bf16 v[0:3], v[140:143], v[144:147], v[0:3]
	s_waitcnt lgkmcnt(4)
	v_mfma_f32_16x16x32_bf16 v[0:3], v[148:151], v[152:155], v[0:3]
	s_waitcnt lgkmcnt(2)
	v_mfma_f32_16x16x32_bf16 v[0:3], v[156:159], v[160:163], v[0:3]
	s_waitcnt lgkmcnt(0)
	v_mfma_f32_16x16x32_bf16 v[0:3], v[164:167], v[168:171], v[0:3]
	s_waitcnt lgkmcnt(0)
	s_barrier
	s_waitcnt vmcnt(9)
	ds_write_b128 v129, v[64:67] offset:36864
	s_waitcnt vmcnt(8)
	ds_write_b128 v129, v[68:71] offset:45056
	s_waitcnt vmcnt(7)
	ds_write_b128 v129, v[72:75] offset:53248
	s_waitcnt vmcnt(6)
	ds_write_b128 v129, v[76:79] offset:61440
	s_waitcnt vmcnt(5)
	ds_write_b128 v130, v[80:83] offset:36864
	global_load_dwordx4 v[104:107], v124, s[98:99]
	global_load_dwordx4 v[108:111], v125, s[98:99]
	global_load_dwordx4 v[112:115], v126, s[98:99]
	global_load_dwordx4 v[116:119], v127, s[98:99]
	global_load_dwordx4 v[120:123], v128, s[96:97]
	s_add_u32 s98, s98, 0x100
	s_addc_u32 s99, s99, 0
	s_add_u32 s96, s96, 0x100
	s_addc_u32 s97, s97, 0
	ds_read_b128 v[140:143], v135
	ds_read_b128 v[144:147], v131
	ds_read_b128 v[148:151], v136
	ds_read_b128 v[152:155], v132
	ds_read_b128 v[156:159], v137
	ds_read_b128 v[160:163], v133
	ds_read_b128 v[164:167], v138
	ds_read_b128 v[168:171], v134
	s_waitcnt lgkmcnt(6)
	v_mfma_f32_16x16x32_bf16 v[0:3], v[140:143], v[144:147], v[0:3]
	s_waitcnt lgkmcnt(4)
	v_mfma_f32_16x16x32_bf16 v[0:3], v[148:151], v[152:155], v[0:3]
	s_waitcnt lgkmcnt(2)
	v_mfma_f32_16x16x32_bf16 v[0:3], v[156:159], v[160:163], v[0:3]
	s_waitcnt lgkmcnt(0)
	v_mfma_f32_16x16x32_bf16 v[0:3], v[164:167], v[168:171], v[0:3]
	s_waitcnt lgkmcnt(0)
	s_barrier
	s_waitcnt vmcnt(9)
	ds_write_b128 v129, v[84:87]
	s_waitcnt vmcnt(8)
	ds_write_b128 v129, v[88:91] offset:8192
	s_waitcnt vmcnt(7)
	ds_write_b128 v129, v[92:95] offset:16384
	s_waitcnt vmcnt(6)
	ds_write_b128 v129, v[96:99] offset:24576
	s_waitcnt vmcnt(5)
	ds_write_b128 v130, v[100:103]
	global_load_dwordx4 v[64:67], v124, s[98:99]
	global_load_dwordx4 v[68:71], v125, s[98:99]
	global_load_dwordx4 v[72:75], v126, s[98:99]
	global_load_dwordx4 v[76:79], v127, s[98:99]
	global_load_dwordx4 v[80:83], v128, s[96:97]
	s_add_u32 s98, s98, 0x100
	s_addc_u32 s99, s99, 0
	s_add_u32 s96, s96, 0x100
	s_addc_u32 s97, s97, 0
	ds_read_b128 v[140:143], v135 offset:36864
	ds_read_b128 v[144:147], v131 offset:36864
	ds_read_b128 v[148:151], v136 offset:36864
	ds_read_b128 v[152:155], v132 offset:36864
	ds_read_b128 v[156:159], v137 offset:36864
	ds_read_b128 v[160:163], v133 offset:36864
	ds_read_b128 v[164:167], v138 offset:36864
	ds_read_b128 v[168:171], v134 offset:36864
	s_waitcnt lgkmcnt(6)
	v_mfma_f32_16x16x32_bf16 v[0:3], v[140:143], v[144:147], v[0:3]
	s_waitcnt lgkmcnt(4)
	v_mfma_f32_16x16x32_bf16 v[0:3], v[148:151], v[152:155], v[0:3]
	s_waitcnt lgkmcnt(2)
	v_mfma_f32_16x16x32_bf16 v[0:3], v[156:159], v[160:163], v[0:3]
	s_waitcnt lgkmcnt(0)
	v_mfma_f32_16x16x32_bf16 v[0:3], v[164:167], v[168:171], v[0:3]
	s_waitcnt lgkmcnt(0)
	s_barrier
; template <int MODE>
; __device__ __forceinline__ void sgemm_sample(LAS unsigned char* lds, const bf16_t* A, const bf16_t* Bt, int K, const float* resid, float* out, bf16_t* xb, float* ssq_out, const float* ssq_in) {
;     ...
; #pragma unroll 8
;         for (int ks = 0; ks < K / 32; ++ks) {
;             const bf16x8 a = *(const bf16x8*)(ap + ks * 32); const bf16x8 b = *(const bf16x8*)(bp + ks * 32);
;             acc = __builtin_amdgcn_mfma_f32_16x16x32_bf16(b, a, acc, 0, 0, 0);
;         }
	s_waitcnt vmcnt(9)
	ds_write_b128 v129, v[104:107] offset:36864
	s_waitcnt vmcnt(8)
	ds_write_b128 v129, v[108:111] offset:45056
	s_waitcnt vmcnt(7)
	ds_write_b128 v129, v[112:115] offset:53248
	s_waitcnt vmcnt(6)
	ds_write_b128 v129, v[116:119] offset:61440
	s_waitcnt vmcnt(5)
	ds_write_b128 v130, v[120:123] offset:36864
	global_load_dwordx4 v[84:87], v124, s[98:99]
	global_load_dwordx4 v[88:91], v125, s[98:99]
	global_load_dwordx4 v[92:95], v126, s[98:99]
	global_load_dwordx4 v[96:99], v127, s[98:99]
	global_load_dwordx4 v[100:103], v128, s[96:97]
	s_add_u32 s98, s98, 0x100
	s_addc_u32 s99, s99, 0
	s_add_u32 s96, s96, 0x100
	s_addc_u32 s97, s97, 0
	ds_read_b128 v[140:143], v135
	ds_read_b128 v[144:147], v131
	ds_read_b128 v[148:151], v136
	ds_read_b128 v[152:155], v132
	ds_read_b128 v[156:159], v137
	ds_read_b128 v[160:163], v133
	ds_read_b128 v[164:167], v138
	ds_read_b128 v[168:171], v134
	s_waitcnt lgkmcnt(6)
	v_mfma_f32_16x16x32_bf16 v[0:3], v[140:143], v[144:147], v[0:3]
	s_waitcnt lgkmcnt(4)
	v_mfma_f32_16x16x32_bf16 v[0:3], v[148:151], v[152:155], v[0:3]
	s_waitcnt lgkmcnt(2)
	v_mfma_f32_16x16x32_bf16 v[0:3], v[156:159], v[160:163], v[0:3]
	s_waitcnt lgkmcnt(0)
	v_mfma_f32_16x16x32_bf16 v[0:3], v[164:167], v[168:171], v[0:3]
	s_waitcnt lgkmcnt(0)
	s_barrier
	s_waitcnt vmcnt(9)
	ds_write_b128 v129, v[64:67]
	s_waitcnt vmcnt(8)
	ds_write_b128 v129, v[68:71] offset:8192
	s_waitcnt vmcnt(7)
	ds_write_b128 v129, v[72:75] offset:16384
	s_waitcnt vmcnt(6)
	ds_write_b128 v129, v[76:79] offset:24576
	s_waitcnt vmcnt(5)
	ds_write_b128 v130, v[80:83]
	global_load_dwordx4 v[104:107], v124, s[98:99]
	global_load_dwordx4 v[108:111], v125, s[98:99]
	global_load_dwordx4 v[112:115], v126, s[98:99]
	global_load_dwordx4 v[116:119], v127, s[98:99]
	global_load_dwordx4 v[120:123], v128, s[96:97]
	s_add_u32 s98, s98, 0x100
	s_addc_u32 s99, s99, 0
	s_add_u32 s96, s96, 0x100
	s_addc_u32 s97, s97, 0
	ds_read_b128 v[140:143], v135 offset:36864
	ds_read_b128 v[144:147], v131 offset:36864
	ds_read_b128 v[148:151], v136 offset:36864
	ds_read_b128 v[152:155], v132 offset:36864
	ds_read_b128 v[156:159], v137 offset:36864
	ds_read_b128 v[160:163], v133 offset:36864
	ds_read_b128 v[164:167], v138 offset:36864
	ds_read_b128 v[168:171], v134 offset:36864
	s_waitcnt lgkmcnt(6)
	v_mfma_f32_16x16x32_bf16 v[0:3], v[140:143], v[144:147], v[0:3]
	s_waitcnt lgkmcnt(4)
	v_mfma_f32_16x16x32_bf16 v[0:3], v[148:151], v[152:155], v[0:3]
	s_waitcnt lgkmcnt(2)
	v_mfma_f32_16x16x32_bf16 v[0:3], v[156:159], v[160:163], v[0:3]
	s_waitcnt lgkmcnt(0)
	v_mfma_f32_16x16x32_bf16 v[0:3], v[164:167], v[168:171], v[0:3]
	s_waitcnt lgkmcnt(0)
	s_barrier
	s_waitcnt vmcnt(9)
	ds_write_b128 v129, v[84:87] offset:36864
	s_waitcnt vmcnt(8)
	ds_write_b128 v129, v[88:91] offset:45056
	s_waitcnt vmcnt(7)
	ds_write_b128 v129, v[92:95] offset:53248
	s_waitcnt vmcnt(6)
	ds_write_b128 v129, v[96:99] offset:61440
	s_waitcnt vmcnt(5)
	ds_write_b128 v130, v[100:103] offset:36864
	global_load_dwordx4 v[64:67], v124, s[98:99]
	global_load_dwordx4 v[68:71], v125, s[98:99]
	global_load_dwordx4 v[72:75], v126, s[98:99]
	global_load_dwordx4 v[76:79], v127, s[98:99]
	global_load_dwordx4 v[80:83], v128, s[96:97]
	s_add_u32 s98, s98, 0x100
	s_addc_u32 s99, s99, 0
	s_add_u32 s96, s96, 0x100
	s_addc_u32 s97, s97, 0
	ds_read_b128 v[140:143], v135
	ds_read_b128 v[144:147], v131
	ds_read_b128 v[148:151], v136
	ds_read_b128 v[152:155], v132
	ds_read_b128 v[156:159], v137
	ds_read_b128 v[160:163], v133
	ds_read_b128 v[164:167], v138
	ds_read_b128 v[168:171], v134
	s_waitcnt lgkmcnt(6)
	v_mfma_f32_16x16x32_bf16 v[0:3], v[140:143], v[144:147], v[0:3]
	s_waitcnt lgkmcnt(4)
	v_mfma_f32_16x16x32_bf16 v[0:3], v[148:151], v[152:155], v[0:3]
	s_waitcnt lgkmcnt(2)
	v_mfma_f32_16x16x32_bf16 v[0:3], v[156:159], v[160:163], v[0:3]
	s_waitcnt lgkmcnt(0)
	v_mfma_f32_16x16x32_bf16 v[0:3], v[164:167], v[168:171], v[0:3]
	s_waitcnt lgkmcnt(0)
	s_barrier
	s_waitcnt vmcnt(9)
	ds_write_b128 v129, v[104:107]
	s_waitcnt vmcnt(8)
	ds_write_b128 v129, v[108:111] offset:8192
	s_waitcnt vmcnt(7)
	ds_write_b128 v129, v[112:115] offset:16384
	s_waitcnt vmcnt(6)
	ds_write_b128 v129, v[116:119] offset:24576
	s_waitcnt vmcnt(5)
	ds_write_b128 v130, v[120:123]
	global_load_dwordx4 v[84:87], v124, s[98:99]
	global_load_dwordx4 v[88:91], v125, s[98:99]
	global_load_dwordx4 v[92:95], v126, s[98:99]
	global_load_dwordx4 v[96:99], v127, s[98:99]
	global_load_dwordx4 v[100:103], v128, s[96:97]
	s_add_u32 s98, s98, 0x100
	s_addc_u32 s99, s99, 0
	s_add_u32 s96, s96, 0x100
	s_addc_u32 s97, s97, 0
	ds_read_b128 v[140:143], v135 offset:36864
	ds_read_b128 v[144:147], v131 offset:36864
	ds_read_b128 v[148:151], v136 offset:36864
	ds_read_b128 v[152:155], v132 offset:36864
	ds_read_b128 v[156:159], v137 offset:36864
	ds_read_b128 v[160:163], v133 offset:36864
	ds_read_b128 v[164:167], v138 offset:36864
	ds_read_b128 v[168:171], v134 offset:36864
	s_waitcnt lgkmcnt(6)
	v_mfma_f32_16x16x32_bf16 v[0:3], v[140:143], v[144:147], v[0:3]
	s_waitcnt lgkmcnt(4)
	v_mfma_f32_16x16x32_bf16 v[0:3], v[148:151], v[152:155], v[0:3]
	s_waitcnt lgkmcnt(2)
	v_mfma_f32_16x16x32_bf16 v[0:3], v[156:159], v[160:163], v[0:3]
	s_waitcnt lgkmcnt(0)
	v_mfma_f32_16x16x32_bf16 v[0:3], v[164:167], v[168:171], v[0:3]
	s_waitcnt lgkmcnt(0)
	s_barrier
; template <int MODE>
; __device__ __forceinline__ void sgemm_sample(LAS unsigned char* lds, const bf16_t* A, const bf16_t* Bt, int K, const float* resid, float* out, bf16_t* xb, float* ssq_out, const float* ssq_in) {
;     ...
; #pragma unroll 8
;         for (int ks = 0; ks < K / 32; ++ks) {
;             const bf16x8 a = *(const bf16x8*)(ap + ks * 32); const bf16x8 b = *(const bf16x8*)(bp + ks * 32);
;             acc = __builtin_amdgcn_mfma_f32_16x16x32_bf16(b, a, acc, 0, 0, 0);
;         }
	s_waitcnt vmcnt(9)
	ds_write_b128 v129, v[64:67] offset:36864
	s_waitcnt vmcnt(8)
	ds_write_b128 v129, v[68:71] offset:45056
	s_waitcnt vmcnt(7)
	ds_write_b128 v129, v[72:75] offset:53248
	s_waitcnt vmcnt(6)
	ds_write_b128 v129, v[76:79] offset:61440
	s_waitcnt vmcnt(5)
	ds_write_b128 v130, v[80:83] offset:36864
	global_load_dwordx4 v[104:107], v124, s[98:99]
	global_load_dwordx4 v[108:111], v125, s[98:99]
	global_load_dwordx4 v[112:115], v126, s[98:99]
	global_load_dwordx4 v[116:119], v127, s[98:99]
	global_load_dwordx4 v[120:123], v128, s[96:97]
	s_add_u32 s98, s98, 0x100
	s_addc_u32 s99, s99, 0
	s_add_u32 s96, s96, 0x100
	s_addc_u32 s97, s97, 0
	ds_read_b128 v[140:143], v135
	ds_read_b128 v[144:147], v131
	ds_read_b128 v[148:151], v136
	ds_read_b128 v[152:155], v132
	ds_read_b128 v[156:159], v137
	ds_read_b128 v[160:163], v133
	ds_read_b128 v[164:167], v138
	ds_read_b128 v[168:171], v134
	s_waitcnt lgkmcnt(6)
	v_mfma_f32_16x16x32_bf16 v[0:3], v[140:143], v[144:147], v[0:3]
	s_waitcnt lgkmcnt(4)
	v_mfma_f32_16x16x32_bf16 v[0:3], v[148:151], v[152:155], v[0:3]
	s_waitcnt lgkmcnt(2)
	v_mfma_f32_16x16x32_bf16 v[0:3], v[156:159], v[160:163], v[0:3]
	s_waitcnt lgkmcnt(0)
	v_mfma_f32_16x16x32_bf16 v[0:3], v[164:167], v[168:171], v[0:3]
	s_waitcnt lgkmcnt(0)
	s_barrier
	s_waitcnt vmcnt(9)
	ds_write_b128 v129, v[84:87]
	s_waitcnt vmcnt(8)
	ds_write_b128 v129, v[88:91] offset:8192
	s_waitcnt vmcnt(7)
	ds_write_b128 v129, v[92:95] offset:16384
	s_waitcnt vmcnt(6)
	ds_write_b128 v129, v[96:99] offset:24576
	s_waitcnt vmcnt(5)
	ds_write_b128 v130, v[100:103]
	global_load_dwordx4 v[64:67], v124, s[98:99]
	global_load_dwordx4 v[68:71], v125, s[98:99]
	global_load_dwordx4 v[72:75], v126, s[98:99]
	global_load_dwordx4 v[76:79], v127, s[98:99]
	global_load_dwordx4 v[80:83], v128, s[96:97]
	s_add_u32 s98, s98, 0x100
	s_addc_u32 s99, s99, 0
	s_add_u32 s96, s96, 0x100
	s_addc_u32 s97, s97, 0
	ds_read_b128 v[140:143], v135 offset:36864
	ds_read_b128 v[144:147], v131 offset:36864
	ds_read_b128 v[148:151], v136 offset:36864
	ds_read_b128 v[152:155], v132 offset:36864
	ds_read_b128 v[156:159], v137 offset:36864
	ds_read_b128 v[160:163], v133 offset:36864
	ds_read_b128 v[164:167], v138 offset:36864
	ds_read_b128 v[168:171], v134 offset:36864
	s_waitcnt lgkmcnt(6)
	v_mfma_f32_16x16x32_bf16 v[0:3], v[140:143], v[144:147], v[0:3]
	s_waitcnt lgkmcnt(4)
	v_mfma_f32_16x16x32_bf16 v[0:3], v[148:151], v[152:155], v[0:3]
	s_waitcnt lgkmcnt(2)
	v_mfma_f32_16x16x32_bf16 v[0:3], v[156:159], v[160:163], v[0:3]
	s_waitcnt lgkmcnt(0)
	v_mfma_f32_16x16x32_bf16 v[0:3], v[164:167], v[168:171], v[0:3]
	s_waitcnt lgkmcnt(0)
	s_barrier
	s_waitcnt vmcnt(9)
	ds_write_b128 v129, v[104:107] offset:36864
	s_waitcnt vmcnt(8)
	ds_write_b128 v129, v[108:111] offset:45056
	s_waitcnt vmcnt(7)
	ds_write_b128 v129, v[112:115] offset:53248
	s_waitcnt vmcnt(6)
	ds_write_b128 v129, v[116:119] offset:61440
	s_waitcnt vmcnt(5)
	ds_write_b128 v130, v[120:123] offset:36864
	global_load_dwordx4 v[84:87], v124, s[98:99]
	global_load_dwordx4 v[88:91], v125, s[98:99]
	global_load_dwordx4 v[92:95], v126, s[98:99]
	global_load_dwordx4 v[96:99], v127, s[98:99]
	global_load_dwordx4 v[100:103], v128, s[96:97]
	s_add_u32 s98, s98, 0x100
	s_addc_u32 s99, s99, 0
	s_add_u32 s96, s96, 0x100
	s_addc_u32 s97, s97, 0
	ds_read_b128 v[140:143], v135
	ds_read_b128 v[144:147], v131
	ds_read_b128 v[148:151], v136
	ds_read_b128 v[152:155], v132
	ds_read_b128 v[156:159], v137
	ds_read_b128 v[160:163], v133
	ds_read_b128 v[164:167], v138
	ds_read_b128 v[168:171], v134
	s_waitcnt lgkmcnt(6)
	v_mfma_f32_16x16x32_bf16 v[0:3], v[140:143], v[144:147], v[0:3]
	s_waitcnt lgkmcnt(4)
	v_mfma_f32_16x16x32_bf16 v[0:3], v[148:151], v[152:155], v[0:3]
	s_waitcnt lgkmcnt(2)
	v_mfma_f32_16x16x32_bf16 v[0:3], v[156:159], v[160:163], v[0:3]
	s_waitcnt lgkmcnt(0)
	v_mfma_f32_16x16x32_bf16 v[0:3], v[164:167], v[168:171], v[0:3]
	s_waitcnt lgkmcnt(0)
	s_barrier
	s_waitcnt vmcnt(9)
	ds_write_b128 v129, v[64:67]
	s_waitcnt vmcnt(8)
	ds_write_b128 v129, v[68:71] offset:8192
	s_waitcnt vmcnt(7)
	ds_write_b128 v129, v[72:75] offset:16384
	s_waitcnt vmcnt(6)
	ds_write_b128 v129, v[76:79] offset:24576
	s_waitcnt vmcnt(5)
	ds_write_b128 v130, v[80:83]
	global_load_dwordx4 v[104:107], v124, s[98:99]
	global_load_dwordx4 v[108:111], v125, s[98:99]
	global_load_dwordx4 v[112:115], v126, s[98:99]
	global_load_dwordx4 v[116:119], v127, s[98:99]
	global_load_dwordx4 v[120:123], v128, s[96:97]
	s_add_u32 s98, s98, 0x100
	s_addc_u32 s99, s99, 0
	s_add_u32 s96, s96, 0x100
	s_addc_u32 s97, s97, 0
	ds_read_b128 v[140:143], v135 offset:36864
	ds_read_b128 v[144:147], v131 offset:36864
	ds_read_b128 v[148:151], v136 offset:36864
	ds_read_b128 v[152:155], v132 offset:36864
	ds_read_b128 v[156:159], v137 offset:36864
	ds_read_b128 v[160:163], v133 offset:36864
	ds_read_b128 v[164:167], v138 offset:36864
	ds_read_b128 v[168:171], v134 offset:36864
	s_waitcnt lgkmcnt(6)
	v_mfma_f32_16x16x32_bf16 v[0:3], v[140:143], v[144:147], v[0:3]
	s_waitcnt lgkmcnt(4)
	v_mfma_f32_16x16x32_bf16 v[0:3], v[148:151], v[152:155], v[0:3]
	s_waitcnt lgkmcnt(2)
	v_mfma_f32_16x16x32_bf16 v[0:3], v[156:159], v[160:163], v[0:3]
	s_waitcnt lgkmcnt(0)
	v_mfma_f32_16x16x32_bf16 v[0:3], v[164:167], v[168:171], v[0:3]
	s_waitcnt lgkmcnt(0)
	s_barrier
; __device__ __forceinline__ unsigned cvt_pk_bf16(float lo, float hi) { f32x2 f = {lo, hi}; bf16x2_t v = __builtin_convertvector(f, bf16x2_t); return __builtin_bit_cast(unsigned, v); }
; template <int MODE>
; __device__ __forceinline__ void sgemm_sample(LAS unsigned char* lds, const bf16_t* A, const bf16_t* Bt, int K, const float* resid, float* out, bf16_t* xb, float* ssq_out, const float* ssq_in) {
;     ...
; #pragma unroll 8
;         for (int ks = 0; ks < K / 32; ++ks) {
;             const bf16x8 a = *(const bf16x8*)(ap + ks * 32); const bf16x8 b = *(const bf16x8*)(bp + ks * 32);
;             acc = __builtin_amdgcn_mfma_f32_16x16x32_bf16(b, a, acc, 0, 0, 0);
;         }
;         if (MODE == 0) {
;             const f32x4 x = *(const f32x4*)(resid + (size_t)(row - NTOKP) * D + col0) + acc;
;             *(f32x4*)(out + (size_t)row * D + col0) = x;
;             if (xb) { u32x2 wv; wv.x = cvt_pk_bf16(x[0], x[1]); wv.y = cvt_pk_bf16(x[2], x[3]); *(u32x2*)(xb + (size_t)row * D + col0) = wv; }
	s_waitcnt vmcnt(9)
	ds_write_b128 v129, v[84:87] offset:36864
	s_waitcnt vmcnt(8)
	ds_write_b128 v129, v[88:91] offset:45056
	s_waitcnt vmcnt(7)
	ds_write_b128 v129, v[92:95] offset:53248
	s_waitcnt vmcnt(6)
	ds_write_b128 v129, v[96:99] offset:61440
	s_waitcnt vmcnt(5)
	ds_write_b128 v130, v[100:103] offset:36864
	global_load_dwordx4 v[64:67], v124, s[98:99]
	global_load_dwordx4 v[68:71], v125, s[98:99]
	global_load_dwordx4 v[72:75], v126, s[98:99]
	global_load_dwordx4 v[76:79], v127, s[98:99]
	global_load_dwordx4 v[80:83], v128, s[96:97]
	s_add_u32 s98, s98, 0x100
	s_addc_u32 s99, s99, 0
	s_add_u32 s96, s96, 0x100
	s_addc_u32 s97, s97, 0
	ds_read_b128 v[140:143], v135
	ds_read_b128 v[144:147], v131
	ds_read_b128 v[148:151], v136
	ds_read_b128 v[152:155], v132
	ds_read_b128 v[156:159], v137
	ds_read_b128 v[160:163], v133
	ds_read_b128 v[164:167], v138
	ds_read_b128 v[168:171], v134
	s_waitcnt lgkmcnt(6)
	v_mfma_f32_16x16x32_bf16 v[0:3], v[140:143], v[144:147], v[0:3]
	s_waitcnt lgkmcnt(4)
	v_mfma_f32_16x16x32_bf16 v[0:3], v[148:151], v[152:155], v[0:3]
	s_waitcnt lgkmcnt(2)
	v_mfma_f32_16x16x32_bf16 v[0:3], v[156:159], v[160:163], v[0:3]
	s_waitcnt lgkmcnt(0)
	v_mfma_f32_16x16x32_bf16 v[0:3], v[164:167], v[168:171], v[0:3]
	s_waitcnt lgkmcnt(0)
	s_barrier
	s_waitcnt vmcnt(9)
	ds_write_b128 v129, v[104:107]
	s_waitcnt vmcnt(8)
	ds_write_b128 v129, v[108:111] offset:8192
	s_waitcnt vmcnt(7)
	ds_write_b128 v129, v[112:115] offset:16384
	s_waitcnt vmcnt(6)
	ds_write_b128 v129, v[116:119] offset:24576
	s_waitcnt vmcnt(5)
	ds_write_b128 v130, v[120:123]
	ds_read_b128 v[140:143], v135 offset:36864
	ds_read_b128 v[144:147], v131 offset:36864
	ds_read_b128 v[148:151], v136 offset:36864
	ds_read_b128 v[152:155], v132 offset:36864
	ds_read_b128 v[156:159], v137 offset:36864
	ds_read_b128 v[160:163], v133 offset:36864
	ds_read_b128 v[164:167], v138 offset:36864
	ds_read_b128 v[168:171], v134 offset:36864
	s_waitcnt lgkmcnt(6)
	v_mfma_f32_16x16x32_bf16 v[0:3], v[140:143], v[144:147], v[0:3]
	s_waitcnt lgkmcnt(4)
	v_mfma_f32_16x16x32_bf16 v[0:3], v[148:151], v[152:155], v[0:3]
	s_waitcnt lgkmcnt(2)
	v_mfma_f32_16x16x32_bf16 v[0:3], v[156:159], v[160:163], v[0:3]
	s_waitcnt lgkmcnt(0)
	v_mfma_f32_16x16x32_bf16 v[0:3], v[164:167], v[168:171], v[0:3]
	s_waitcnt lgkmcnt(0)
	s_barrier
	s_waitcnt vmcnt(4)
	ds_write_b128 v129, v[64:67] offset:36864
	s_waitcnt vmcnt(3)
	ds_write_b128 v129, v[68:71] offset:45056
	s_waitcnt vmcnt(2)
	ds_write_b128 v129, v[72:75] offset:53248
	s_waitcnt vmcnt(1)
	ds_write_b128 v129, v[76:79] offset:61440
	s_waitcnt vmcnt(0)
	ds_write_b128 v130, v[80:83] offset:36864
	ds_read_b128 v[140:143], v135
	ds_read_b128 v[144:147], v131
	ds_read_b128 v[148:151], v136
	ds_read_b128 v[152:155], v132
	ds_read_b128 v[156:159], v137
	ds_read_b128 v[160:163], v133
	ds_read_b128 v[164:167], v138
	ds_read_b128 v[168:171], v134
	s_waitcnt lgkmcnt(6)
	v_mfma_f32_16x16x32_bf16 v[0:3], v[140:143], v[144:147], v[0:3]
	s_waitcnt lgkmcnt(4)
	v_mfma_f32_16x16x32_bf16 v[0:3], v[148:151], v[152:155], v[0:3]
	s_waitcnt lgkmcnt(2)
	v_mfma_f32_16x16x32_bf16 v[0:3], v[156:159], v[160:163], v[0:3]
	s_waitcnt lgkmcnt(0)
	v_mfma_f32_16x16x32_bf16 v[0:3], v[164:167], v[168:171], v[0:3]
	s_waitcnt lgkmcnt(0)
	s_barrier
	ds_read_b128 v[140:143], v135 offset:36864
	ds_read_b128 v[144:147], v131 offset:36864
	ds_read_b128 v[148:151], v136 offset:36864
	ds_read_b128 v[152:155], v132 offset:36864
	ds_read_b128 v[156:159], v137 offset:36864
	ds_read_b128 v[160:163], v133 offset:36864
	ds_read_b128 v[164:167], v138 offset:36864
	ds_read_b128 v[168:171], v134 offset:36864
	s_waitcnt lgkmcnt(6)
	v_mfma_f32_16x16x32_bf16 v[0:3], v[140:143], v[144:147], v[0:3]
	s_waitcnt lgkmcnt(4)
	v_mfma_f32_16x16x32_bf16 v[0:3], v[148:151], v[152:155], v[0:3]
	s_waitcnt lgkmcnt(2)
	v_mfma_f32_16x16x32_bf16 v[0:3], v[156:159], v[160:163], v[0:3]
	s_waitcnt lgkmcnt(0)
	v_mfma_f32_16x16x32_bf16 v[0:3], v[164:167], v[168:171], v[0:3]
	s_nop 7
	s_branch .Lsgx3_done
.LBB0_1349:
	v_lshl_add_u64 v[18:19], v[10:11], 0, s[0:1]
	v_add_co_u32_e32 v54, vcc, 0x22c0000, v18
	v_lshl_add_u64 v[20:21], v[12:13], 0, s[0:1]
	s_nop 0
	v_addc_co_u32_e32 v55, vcc, 0, v19, vcc
	v_add_co_u32_e32 v56, vcc, 0x1d40000, v20
	s_add_u32 s0, s0, 0x200
	s_nop 0
	v_addc_co_u32_e32 v57, vcc, 0, v21, vcc
	global_load_dwordx4 v[18:21], v[54:55], off
	global_load_dwordx4 v[22:25], v[54:55], off offset:64
	global_load_dwordx4 v[26:29], v[54:55], off offset:128
	global_load_dwordx4 v[30:33], v[54:55], off offset:192
	global_load_dwordx4 v[34:37], v[54:55], off offset:256
	global_load_dwordx4 v[38:41], v[56:57], off
	global_load_dwordx4 v[42:45], v[56:57], off offset:64
	global_load_dwordx4 v[46:49], v[56:57], off offset:128
	global_load_dwordx4 v[50:53], v[56:57], off offset:192
	s_addc_u32 s1, s1, 0
	s_cmpk_eq_i32 s0, 0x1600
	s_waitcnt vmcnt(3)
	v_mfma_f32_16x16x32_bf16 v[0:3], v[38:41], v[18:21], v[0:3]
	global_load_dwordx4 v[18:21], v[56:57], off offset:256
	s_waitcnt vmcnt(3)
	v_mfma_f32_16x16x32_bf16 v[0:3], v[42:45], v[22:25], v[0:3]
	global_load_dwordx4 v[22:25], v[56:57], off offset:320
	s_waitcnt vmcnt(3)
	v_mfma_f32_16x16x32_bf16 v[0:3], v[46:49], v[26:29], v[0:3]
	global_load_dwordx4 v[26:29], v[54:55], off offset:320
	s_waitcnt vmcnt(3)
	v_mfma_f32_16x16x32_bf16 v[0:3], v[50:53], v[30:33], v[0:3]
	global_load_dwordx4 v[30:33], v[56:57], off offset:384
	global_load_dwordx4 v[38:41], v[54:55], off offset:384
	s_waitcnt vmcnt(4)
	v_mfma_f32_16x16x32_bf16 v[0:3], v[18:21], v[34:37], v[0:3]
	global_load_dwordx4 v[18:21], v[56:57], off offset:448
	s_waitcnt vmcnt(3)
	v_mfma_f32_16x16x32_bf16 v[0:3], v[22:25], v[26:29], v[0:3]
	global_load_dwordx4 v[22:25], v[54:55], off offset:448
	s_waitcnt vmcnt(2)
	v_mfma_f32_16x16x32_bf16 v[0:3], v[30:33], v[38:41], v[0:3]
	s_waitcnt vmcnt(0)
	v_mfma_f32_16x16x32_bf16 v[0:3], v[18:21], v[22:25], v[0:3]
	s_cbranch_scc0 .LBB0_1349
.Lsgx3_done:
	v_or_b32_e32 v4, s10, v15
	v_lshlrev_b64 v[12:13], 12, v[8:9]
	v_lshl_add_u64 v[8:9], s[8:9], 0, v[12:13]
	v_lshlrev_b32_e32 v4, 2, v4
	v_lshl_add_u64 v[8:9], v[8:9], 0, v[4:5]
	v_add_co_u32_e32 v8, vcc, 0xf8000000, v8
	s_add_i32 s3, s3, s4
	s_nop 0
	v_addc_co_u32_e32 v9, vcc, -1, v9, vcc
	global_load_dwordx4 v[8:11], v[8:9], off
	v_lshl_add_u64 v[12:13], s[90:91], 0, v[12:13]
	v_lshl_add_u64 v[12:13], v[12:13], 0, v[4:5]
	s_cmpk_gt_i32 s3, 0x7ff
	s_waitcnt vmcnt(0)
	v_pk_add_f32 v[2:3], v[2:3], v[10:11]
	v_pk_add_f32 v[0:1], v[0:1], v[8:9]
	global_store_dwordx4 v[12:13], v[0:3], off
	s_cbranch_scc0 .LBB0_1348
